# convert_layer(1): tr_item loops keep 16 loads in flight; compression-bias partial-sum loop issues its 34 loads together (same fma order)
# speedup vs baseline: 1.0109x; 1.0039x over previous
; #define LAS __attribute__((address_space(3)))
; #define LDS_WAIT() asm volatile("s_waitcnt lgkmcnt(0)" ::: "memory")
; __device__ __forceinline__ void tr_item(const float* W, int ldw, int src_col, int nvalid, int k0, bf16_t* WT, int ldt, int dst_row, int dst_k, LAS float* scr, int lane) {
; #pragma unroll 8
;     for (int i = 0; i < 32; ++i) { const int kk = 2 * i + (lane >> 5), c = lane & 31; scr[kk * 33 + c] = (c < nvalid) ? W[(size_t)(k0 + kk) * ldw + src_col + c] : 0.f; }
;     LDS_WAIT();
.LBB0_1422:
	s_lshl_b32 s11, s13, 1
	s_lshl_b32 s10, s3, 1
	v_or_b32_e32 v49, s11, v2
	v_or_b32_e32 v0, s10, v3
	v_add_u32_e32 v54, s12, v49
	v_add_u32_e32 v52, s6, v0
	v_ashrrev_i32_e32 v55, 31, v54
	v_ashrrev_i32_e32 v53, 31, v52
	v_lshlrev_b64 v[54:55], 12, v[54:55]
	v_lshlrev_b64 v[52:53], 12, v[52:53]
	v_lshl_add_u64 v[54:55], v[50:51], 0, v[54:55]
	v_lshl_add_u64 v[52:53], v[50:51], 0, v[52:53]
	global_load_dword v132, v[54:55], off
	global_load_dword v133, v[52:53], off
	v_mad_u64_u32 v[52:53], s[18:19], v49, s53, v[6:7]
	v_mad_u64_u32 v[54:55], s[18:19], v0, s53, v[6:7]
	s_add_i32 s19, s11, 4
	s_add_i32 s18, s10, 4
	v_or_b32_e32 v49, s19, v2
	v_or_b32_e32 v0, s18, v3
	s_add_i32 s13, s13, 16
	s_add_i32 s3, s3, 16
	s_add_i32 s17, s17, -16
	v_mov_b32_e32 v148, v52
	v_mov_b32_e32 v149, v54
	v_add_u32_e32 v54, s12, v49
	v_add_u32_e32 v52, s6, v0
	v_ashrrev_i32_e32 v55, 31, v54
	v_ashrrev_i32_e32 v53, 31, v52
	v_lshlrev_b64 v[54:55], 12, v[54:55]
	v_lshlrev_b64 v[52:53], 12, v[52:53]
	v_lshl_add_u64 v[54:55], v[50:51], 0, v[54:55]
	v_lshl_add_u64 v[52:53], v[50:51], 0, v[52:53]
	global_load_dword v134, v[54:55], off
	global_load_dword v135, v[52:53], off
	v_mad_u64_u32 v[52:53], s[18:19], v49, s53, v[6:7]
	v_mad_u64_u32 v[54:55], s[18:19], v0, s53, v[6:7]
	s_add_i32 s19, s11, 8
	s_add_i32 s18, s10, 8
	v_or_b32_e32 v49, s19, v2
	v_or_b32_e32 v0, s18, v3
	v_mov_b32_e32 v150, v52
	v_mov_b32_e32 v151, v54
	v_add_u32_e32 v54, s12, v49
	v_add_u32_e32 v52, s6, v0
	v_ashrrev_i32_e32 v55, 31, v54
	v_ashrrev_i32_e32 v53, 31, v52
	v_lshlrev_b64 v[54:55], 12, v[54:55]
	v_lshlrev_b64 v[52:53], 12, v[52:53]
	v_lshl_add_u64 v[54:55], v[50:51], 0, v[54:55]
	v_lshl_add_u64 v[52:53], v[50:51], 0, v[52:53]
	global_load_dword v136, v[54:55], off
	global_load_dword v137, v[52:53], off
	v_mad_u64_u32 v[52:53], s[18:19], v49, s53, v[6:7]
	v_mad_u64_u32 v[54:55], s[18:19], v0, s53, v[6:7]
	s_add_i32 s19, s11, 12
	s_add_i32 s18, s10, 12
	v_or_b32_e32 v49, s19, v2
	v_or_b32_e32 v0, s18, v3
	v_mov_b32_e32 v152, v52
	v_mov_b32_e32 v153, v54
	v_add_u32_e32 v54, s12, v49
	v_add_u32_e32 v52, s6, v0
	v_ashrrev_i32_e32 v55, 31, v54
	v_ashrrev_i32_e32 v53, 31, v52
	v_lshlrev_b64 v[54:55], 12, v[54:55]
	v_lshlrev_b64 v[52:53], 12, v[52:53]
	v_lshl_add_u64 v[54:55], v[50:51], 0, v[54:55]
	v_lshl_add_u64 v[52:53], v[50:51], 0, v[52:53]
	global_load_dword v138, v[54:55], off
	global_load_dword v139, v[52:53], off
	v_mad_u64_u32 v[52:53], s[18:19], v49, s53, v[6:7]
	v_mad_u64_u32 v[54:55], s[18:19], v0, s53, v[6:7]
	s_add_i32 s19, s11, 16
	s_add_i32 s18, s10, 16
	v_or_b32_e32 v49, s19, v2
	v_or_b32_e32 v0, s18, v3
	v_mov_b32_e32 v154, v52
	v_mov_b32_e32 v155, v54
	v_add_u32_e32 v54, s12, v49
	v_add_u32_e32 v52, s6, v0
	v_ashrrev_i32_e32 v55, 31, v54
	v_ashrrev_i32_e32 v53, 31, v52
	v_lshlrev_b64 v[54:55], 12, v[54:55]
	v_lshlrev_b64 v[52:53], 12, v[52:53]
	v_lshl_add_u64 v[54:55], v[50:51], 0, v[54:55]
	v_lshl_add_u64 v[52:53], v[50:51], 0, v[52:53]
	global_load_dword v140, v[54:55], off
	global_load_dword v141, v[52:53], off
	v_mad_u64_u32 v[52:53], s[18:19], v49, s53, v[6:7]
	v_mad_u64_u32 v[54:55], s[18:19], v0, s53, v[6:7]
	s_add_i32 s19, s11, 20
	s_add_i32 s18, s10, 20
	v_or_b32_e32 v49, s19, v2
	v_or_b32_e32 v0, s18, v3
	v_mov_b32_e32 v156, v52
	v_mov_b32_e32 v157, v54
	v_add_u32_e32 v54, s12, v49
	v_add_u32_e32 v52, s6, v0
	v_ashrrev_i32_e32 v55, 31, v54
	v_ashrrev_i32_e32 v53, 31, v52
	v_lshlrev_b64 v[54:55], 12, v[54:55]
	v_lshlrev_b64 v[52:53], 12, v[52:53]
	v_lshl_add_u64 v[54:55], v[50:51], 0, v[54:55]
	v_lshl_add_u64 v[52:53], v[50:51], 0, v[52:53]
	global_load_dword v142, v[54:55], off
	global_load_dword v143, v[52:53], off
	v_mad_u64_u32 v[52:53], s[18:19], v49, s53, v[6:7]
	v_mad_u64_u32 v[54:55], s[18:19], v0, s53, v[6:7]
	s_add_i32 s19, s11, 24
	s_add_i32 s18, s10, 24
	v_or_b32_e32 v49, s19, v2
	v_or_b32_e32 v0, s18, v3
	s_add_i32 s11, s11, 28
	s_add_i32 s10, s10, 28
	s_cmp_lg_u32 s17, 0
	v_mov_b32_e32 v158, v52
	v_mov_b32_e32 v159, v54
	v_add_u32_e32 v54, s12, v49
	v_add_u32_e32 v52, s6, v0
	v_ashrrev_i32_e32 v55, 31, v54
	v_ashrrev_i32_e32 v53, 31, v52
	v_lshlrev_b64 v[54:55], 12, v[54:55]
	v_lshlrev_b64 v[52:53], 12, v[52:53]
	v_lshl_add_u64 v[54:55], v[50:51], 0, v[54:55]
	v_lshl_add_u64 v[52:53], v[50:51], 0, v[52:53]
	global_load_dword v144, v[54:55], off
	global_load_dword v145, v[52:53], off
	v_mad_u64_u32 v[52:53], s[18:19], v49, s53, v[6:7]
	v_mad_u64_u32 v[54:55], s[18:19], v0, s53, v[6:7]
	v_or_b32_e32 v49, s11, v2
	v_or_b32_e32 v0, s10, v3
	v_mov_b32_e32 v160, v52
	v_mov_b32_e32 v161, v54
	v_add_u32_e32 v54, s12, v49
	v_add_u32_e32 v52, s6, v0
	v_ashrrev_i32_e32 v55, 31, v54
	v_ashrrev_i32_e32 v53, 31, v52
	v_lshlrev_b64 v[54:55], 12, v[54:55]
	v_lshlrev_b64 v[52:53], 12, v[52:53]
	v_lshl_add_u64 v[54:55], v[50:51], 0, v[54:55]
	v_lshl_add_u64 v[52:53], v[50:51], 0, v[52:53]
	global_load_dword v146, v[54:55], off
	global_load_dword v147, v[52:53], off
	v_mad_u64_u32 v[52:53], s[10:11], v49, s53, v[6:7]
	v_mad_u64_u32 v[54:55], s[10:11], v0, s53, v[6:7]
	v_mov_b32_e32 v162, v52
	v_mov_b32_e32 v163, v54
	s_waitcnt vmcnt(15)
	ds_write_b32 v148, v132
	s_waitcnt vmcnt(14)
	ds_write_b32 v149, v133
	s_waitcnt vmcnt(13)
	ds_write_b32 v150, v134
	s_waitcnt vmcnt(12)
	ds_write_b32 v151, v135
	s_waitcnt vmcnt(11)
	ds_write_b32 v152, v136
	s_waitcnt vmcnt(10)
	ds_write_b32 v153, v137
	s_waitcnt vmcnt(9)
	ds_write_b32 v154, v138
	s_waitcnt vmcnt(8)
	ds_write_b32 v155, v139
	s_waitcnt vmcnt(7)
	ds_write_b32 v156, v140
	s_waitcnt vmcnt(6)
	ds_write_b32 v157, v141
	s_waitcnt vmcnt(5)
	ds_write_b32 v158, v142
	s_waitcnt vmcnt(4)
	ds_write_b32 v159, v143
	s_waitcnt vmcnt(3)
	ds_write_b32 v160, v144
	s_waitcnt vmcnt(2)
	ds_write_b32 v161, v145
	s_waitcnt vmcnt(1)
	ds_write_b32 v162, v146
	s_waitcnt vmcnt(0)
	ds_write_b32 v163, v147
	s_cbranch_scc1 .LBB0_1422
; #define LAS __attribute__((address_space(3)))
; __device__ __forceinline__ unsigned cvt_pk_bf16(float lo, float hi) { f32x2_t v = {lo, hi}; bf16x2_t b = __builtin_convertvector(v, bf16x2_t); return __builtin_bit_cast(unsigned, b); }
; #define LDS_WAIT() asm volatile("s_waitcnt lgkmcnt(0)" ::: "memory")
; __device__ __forceinline__ void tr_item(const float* W, int ldw, int src_col, int nvalid, int k0, bf16_t* WT, int ldt, int dst_row, int dst_k, LAS float* scr, int lane) {
;     ...
;     const int c = lane & 7;
; #pragma unroll
;     for (int j = 0; j < 4; ++j) { const int n = (lane >> 3) + 8 * j; const LAS float* s = scr + (8 * c) * 33 + n;
;         u32x4 o; o.x = cvt_pk_bf16(s[0 * 33], s[1 * 33]); o.y = cvt_pk_bf16(s[2 * 33], s[3 * 33]); o.z = cvt_pk_bf16(s[4 * 33], s[5 * 33]); o.w = cvt_pk_bf16(s[6 * 33], s[7 * 33]);
;         *(u32x4*)(WT + (size_t)(dst_row + n) * ldt + dst_k + k0 + 8 * c) = o; }
;     LDS_WAIT();
	s_waitcnt lgkmcnt(0)
	ds_read2_b32 v[56:57], v7 offset0:33 offset1:41
	ds_read2_b32 v[58:59], v7 offset1:8
	ds_read2_b32 v[60:61], v7 offset0:66 offset1:74
	ds_read2_b32 v[62:63], v7 offset0:99 offset1:107
	ds_read2_b32 v[64:65], v7 offset0:132 offset1:140
	ds_read2_b32 v[78:79], v7 offset0:165 offset1:173
	ds_read2_b32 v[80:81], v7 offset0:198 offset1:206
	ds_read2_b32 v[82:83], v7 offset0:231 offset1:239
	s_mov_b32 s13, s7
	v_or_b32_e32 v0, s2, v5
	v_lshl_add_u64 v[54:55], s[12:13], 1, v[10:11]
	v_lshlrev_b32_e32 v0, 11, v0
	v_lshl_add_u64 v[84:85], v[54:55], 0, v[0:1]
	v_or_b32_e32 v0, s2, v35
	s_waitcnt lgkmcnt(6)
	v_cvt_pk_bf16_f32 v50, v58, v56
	s_waitcnt lgkmcnt(4)
	v_cvt_pk_bf16_f32 v51, v60, v62
	s_waitcnt lgkmcnt(2)
	v_cvt_pk_bf16_f32 v52, v64, v78
	s_waitcnt lgkmcnt(0)
	v_cvt_pk_bf16_f32 v53, v80, v82
	v_lshlrev_b32_e32 v0, 11, v0
	global_store_dwordx4 v[84:85], v[50:53], off
	s_nop 1
	v_cvt_pk_bf16_f32 v50, v59, v57
	v_cvt_pk_bf16_f32 v51, v61, v63
	v_cvt_pk_bf16_f32 v52, v65, v79
	v_cvt_pk_bf16_f32 v53, v81, v83
	v_lshl_add_u64 v[56:57], v[54:55], 0, v[0:1]
	global_store_dwordx4 v[56:57], v[50:53], off
	ds_read2_b32 v[56:57], v7 offset0:49 offset1:57
	ds_read2_b32 v[58:59], v7 offset0:16 offset1:24
	ds_read2_b32 v[60:61], v7 offset0:82 offset1:90
	ds_read2_b32 v[62:63], v7 offset0:115 offset1:123
	ds_read2_b32 v[64:65], v7 offset0:148 offset1:156
	ds_read2_b32 v[78:79], v7 offset0:181 offset1:189
	ds_read2_b32 v[80:81], v7 offset0:214 offset1:222
	ds_read2_b32 v[82:83], v7 offset0:247 offset1:255
	v_or_b32_e32 v0, s2, v67
	v_lshlrev_b32_e32 v0, 11, v0
	v_lshl_add_u64 v[84:85], v[54:55], 0, v[0:1]
	v_or_b32_e32 v0, s2, v68
	s_waitcnt lgkmcnt(6)
	v_cvt_pk_bf16_f32 v50, v58, v56
	s_waitcnt lgkmcnt(4)
	v_cvt_pk_bf16_f32 v51, v60, v62
	s_waitcnt lgkmcnt(2)
	v_cvt_pk_bf16_f32 v52, v64, v78
	s_waitcnt lgkmcnt(0)
	v_cvt_pk_bf16_f32 v53, v80, v82
	v_lshlrev_b32_e32 v0, 11, v0
	global_store_dwordx4 v[84:85], v[50:53], off
	v_lshl_add_u64 v[54:55], v[54:55], 0, v[0:1]
	s_mov_b64 s[2:3], 0
	v_cvt_pk_bf16_f32 v50, v59, v57
	v_cvt_pk_bf16_f32 v51, v61, v63
	v_cvt_pk_bf16_f32 v52, v65, v79
	v_cvt_pk_bf16_f32 v53, v81, v83
	global_store_dwordx4 v[54:55], v[50:53], off
	s_waitcnt lgkmcnt(0)

; #define LAS __attribute__((address_space(3)))
; #define LDS_WAIT() asm volatile("s_waitcnt lgkmcnt(0)" ::: "memory")
; __device__ __forceinline__ void tr_item(const float* W, int ldw, int src_col, int nvalid, int k0, bf16_t* WT, int ldt, int dst_row, int dst_k, LAS float* scr, int lane) {
; #pragma unroll 8
;     for (int i = 0; i < 32; ++i) { const int kk = 2 * i + (lane >> 5), c = lane & 31; scr[kk * 33 + c] = (c < nvalid) ? W[(size_t)(k0 + kk) * ldw + src_col + c] : 0.f; }
;     LDS_WAIT();
.LBB0_1426:
	s_lshl_b32 s11, s13, 1
	s_lshl_b32 s10, s6, 1
	v_or_b32_e32 v49, s11, v2
	v_or_b32_e32 v0, s10, v3
	v_add_u32_e32 v54, s12, v49
	v_add_u32_e32 v52, s3, v0
	v_ashrrev_i32_e32 v55, 31, v54
	v_ashrrev_i32_e32 v53, 31, v52
	v_lshlrev_b64 v[54:55], 10, v[54:55]
	v_lshlrev_b64 v[52:53], 10, v[52:53]
	v_lshl_add_u64 v[54:55], v[50:51], 0, v[54:55]
	v_lshl_add_u64 v[52:53], v[50:51], 0, v[52:53]
	global_load_dword v132, v[54:55], off
	global_load_dword v133, v[52:53], off
	v_mad_u64_u32 v[52:53], s[18:19], v49, s53, v[6:7]
	v_mad_u64_u32 v[54:55], s[18:19], v0, s53, v[6:7]
	s_add_i32 s18, s11, 4
	s_add_i32 s17, s10, 4
	v_or_b32_e32 v49, s18, v2
	v_or_b32_e32 v0, s17, v3
	s_add_i32 s17, s10, 8
	s_add_i32 s13, s13, 16
	s_add_i32 s6, s6, 16
	s_add_i32 s16, s16, -16
	v_mov_b32_e32 v148, v52
	v_mov_b32_e32 v149, v54
	v_add_u32_e32 v54, s12, v49
	v_add_u32_e32 v52, s3, v0
	v_ashrrev_i32_e32 v55, 31, v54
	v_ashrrev_i32_e32 v53, 31, v52
	v_lshlrev_b64 v[54:55], 10, v[54:55]
	v_lshlrev_b64 v[52:53], 10, v[52:53]
	v_lshl_add_u64 v[54:55], v[50:51], 0, v[54:55]
	v_lshl_add_u64 v[52:53], v[50:51], 0, v[52:53]
	global_load_dword v134, v[54:55], off
	global_load_dword v135, v[52:53], off
	v_mad_u64_u32 v[52:53], s[18:19], v49, s53, v[6:7]
	v_mad_u64_u32 v[54:55], s[18:19], v0, s53, v[6:7]
	s_add_i32 s18, s11, 8
	s_nop 0
	v_or_b32_e32 v49, s18, v2
	v_or_b32_e32 v0, s17, v3
	s_add_i32 s17, s10, 12
	v_mov_b32_e32 v150, v52
	v_mov_b32_e32 v151, v54
	v_add_u32_e32 v54, s12, v49
	v_add_u32_e32 v52, s3, v0
	v_ashrrev_i32_e32 v55, 31, v54
	v_ashrrev_i32_e32 v53, 31, v52
	v_lshlrev_b64 v[54:55], 10, v[54:55]
	v_lshlrev_b64 v[52:53], 10, v[52:53]
	v_lshl_add_u64 v[54:55], v[50:51], 0, v[54:55]
	v_lshl_add_u64 v[52:53], v[50:51], 0, v[52:53]
	global_load_dword v136, v[54:55], off
	global_load_dword v137, v[52:53], off
	v_mad_u64_u32 v[52:53], s[18:19], v49, s53, v[6:7]
	v_mad_u64_u32 v[54:55], s[18:19], v0, s53, v[6:7]
	s_add_i32 s18, s11, 12
	s_nop 0
	v_or_b32_e32 v49, s18, v2
	v_or_b32_e32 v0, s17, v3
	s_add_i32 s17, s10, 16
	v_mov_b32_e32 v152, v52
	v_mov_b32_e32 v153, v54
	v_add_u32_e32 v54, s12, v49
	v_add_u32_e32 v52, s3, v0
	v_ashrrev_i32_e32 v55, 31, v54
	v_ashrrev_i32_e32 v53, 31, v52
	v_lshlrev_b64 v[54:55], 10, v[54:55]
	v_lshlrev_b64 v[52:53], 10, v[52:53]
	v_lshl_add_u64 v[54:55], v[50:51], 0, v[54:55]
	v_lshl_add_u64 v[52:53], v[50:51], 0, v[52:53]
	global_load_dword v138, v[54:55], off
	global_load_dword v139, v[52:53], off
	v_mad_u64_u32 v[52:53], s[18:19], v49, s53, v[6:7]
	v_mad_u64_u32 v[54:55], s[18:19], v0, s53, v[6:7]
	s_add_i32 s18, s11, 16
	s_nop 0
	v_or_b32_e32 v49, s18, v2
	v_or_b32_e32 v0, s17, v3
	s_add_i32 s17, s10, 20
	v_mov_b32_e32 v154, v52
	v_mov_b32_e32 v155, v54
	v_add_u32_e32 v54, s12, v49
	v_add_u32_e32 v52, s3, v0
	v_ashrrev_i32_e32 v55, 31, v54
	v_ashrrev_i32_e32 v53, 31, v52
	v_lshlrev_b64 v[54:55], 10, v[54:55]
	v_lshlrev_b64 v[52:53], 10, v[52:53]
	v_lshl_add_u64 v[54:55], v[50:51], 0, v[54:55]
	v_lshl_add_u64 v[52:53], v[50:51], 0, v[52:53]
	global_load_dword v140, v[54:55], off
	global_load_dword v141, v[52:53], off
	v_mad_u64_u32 v[52:53], s[18:19], v49, s53, v[6:7]
	v_mad_u64_u32 v[54:55], s[18:19], v0, s53, v[6:7]
	s_add_i32 s18, s11, 20
	s_nop 0
	v_or_b32_e32 v49, s18, v2
	v_or_b32_e32 v0, s17, v3
	s_add_i32 s17, s10, 24
	s_add_i32 s10, s10, 28
	v_mov_b32_e32 v156, v52
	v_mov_b32_e32 v157, v54
	v_add_u32_e32 v54, s12, v49
	v_add_u32_e32 v52, s3, v0
	v_ashrrev_i32_e32 v55, 31, v54
	v_ashrrev_i32_e32 v53, 31, v52
	v_lshlrev_b64 v[54:55], 10, v[54:55]
	v_lshlrev_b64 v[52:53], 10, v[52:53]
	v_lshl_add_u64 v[54:55], v[50:51], 0, v[54:55]
	v_lshl_add_u64 v[52:53], v[50:51], 0, v[52:53]
	global_load_dword v142, v[54:55], off
	global_load_dword v143, v[52:53], off
	v_mad_u64_u32 v[52:53], s[18:19], v49, s53, v[6:7]
	v_mad_u64_u32 v[54:55], s[18:19], v0, s53, v[6:7]
	s_add_i32 s18, s11, 24
	s_nop 0
	v_or_b32_e32 v49, s18, v2
	v_or_b32_e32 v0, s17, v3
	s_add_i32 s11, s11, 28
	s_cmp_lg_u32 s16, 0
	v_mov_b32_e32 v158, v52
	v_mov_b32_e32 v159, v54
	v_add_u32_e32 v54, s12, v49
	v_add_u32_e32 v52, s3, v0
	v_ashrrev_i32_e32 v55, 31, v54
	v_ashrrev_i32_e32 v53, 31, v52
	v_lshlrev_b64 v[54:55], 10, v[54:55]
	v_lshlrev_b64 v[52:53], 10, v[52:53]
	v_lshl_add_u64 v[54:55], v[50:51], 0, v[54:55]
	v_lshl_add_u64 v[52:53], v[50:51], 0, v[52:53]
	global_load_dword v144, v[54:55], off
	global_load_dword v145, v[52:53], off
	v_mad_u64_u32 v[52:53], s[18:19], v49, s53, v[6:7]
	v_mad_u64_u32 v[54:55], s[18:19], v0, s53, v[6:7]
	v_or_b32_e32 v49, s11, v2
	v_or_b32_e32 v0, s10, v3
	v_mov_b32_e32 v160, v52
	v_mov_b32_e32 v161, v54
	v_add_u32_e32 v54, s12, v49
	v_add_u32_e32 v52, s3, v0
	v_ashrrev_i32_e32 v55, 31, v54
	v_ashrrev_i32_e32 v53, 31, v52
	v_lshlrev_b64 v[54:55], 10, v[54:55]
	v_lshlrev_b64 v[52:53], 10, v[52:53]
	v_lshl_add_u64 v[54:55], v[50:51], 0, v[54:55]
	v_lshl_add_u64 v[52:53], v[50:51], 0, v[52:53]
	global_load_dword v146, v[54:55], off
	global_load_dword v147, v[52:53], off
	v_mad_u64_u32 v[52:53], s[10:11], v49, s53, v[6:7]
	v_mad_u64_u32 v[54:55], s[10:11], v0, s53, v[6:7]
	v_mov_b32_e32 v162, v52
	v_mov_b32_e32 v163, v54
	s_waitcnt vmcnt(15)
	ds_write_b32 v148, v132
	s_waitcnt vmcnt(14)
	ds_write_b32 v149, v133
	s_waitcnt vmcnt(13)
	ds_write_b32 v150, v134
	s_waitcnt vmcnt(12)
	ds_write_b32 v151, v135
	s_waitcnt vmcnt(11)
	ds_write_b32 v152, v136
	s_waitcnt vmcnt(10)
	ds_write_b32 v153, v137
	s_waitcnt vmcnt(9)
	ds_write_b32 v154, v138
	s_waitcnt vmcnt(8)
	ds_write_b32 v155, v139
	s_waitcnt vmcnt(7)
	ds_write_b32 v156, v140
	s_waitcnt vmcnt(6)
	ds_write_b32 v157, v141
	s_waitcnt vmcnt(5)
	ds_write_b32 v158, v142
	s_waitcnt vmcnt(4)
	ds_write_b32 v159, v143
	s_waitcnt vmcnt(3)
	ds_write_b32 v160, v144
	s_waitcnt vmcnt(2)
	ds_write_b32 v161, v145
	s_waitcnt vmcnt(1)
	ds_write_b32 v162, v146
	s_waitcnt vmcnt(0)
	ds_write_b32 v163, v147
	s_cbranch_scc1 .LBB0_1426
; #define LAS __attribute__((address_space(3)))
; __device__ __forceinline__ unsigned cvt_pk_bf16(float lo, float hi) { f32x2_t v = {lo, hi}; bf16x2_t b = __builtin_convertvector(v, bf16x2_t); return __builtin_bit_cast(unsigned, b); }
; #define LDS_WAIT() asm volatile("s_waitcnt lgkmcnt(0)" ::: "memory")
; __device__ __forceinline__ void tr_item(const float* W, int ldw, int src_col, int nvalid, int k0, bf16_t* WT, int ldt, int dst_row, int dst_k, LAS float* scr, int lane) {
;     ...
;     const int c = lane & 7;
; #pragma unroll
;     for (int j = 0; j < 4; ++j) { const int n = (lane >> 3) + 8 * j; const LAS float* s = scr + (8 * c) * 33 + n;
;         u32x4 o; o.x = cvt_pk_bf16(s[0 * 33], s[1 * 33]); o.y = cvt_pk_bf16(s[2 * 33], s[3 * 33]); o.z = cvt_pk_bf16(s[4 * 33], s[5 * 33]); o.w = cvt_pk_bf16(s[6 * 33], s[7 * 33]);
;         *(u32x4*)(WT + (size_t)(dst_row + n) * ldt + dst_k + k0 + 8 * c) = o; }
;     LDS_WAIT();
	s_waitcnt lgkmcnt(0)
	ds_read2_b32 v[56:57], v7 offset0:33 offset1:41
	ds_read2_b32 v[58:59], v7 offset1:8
	ds_read2_b32 v[60:61], v7 offset0:66 offset1:74
	ds_read2_b32 v[62:63], v7 offset0:99 offset1:107
	ds_read2_b32 v[64:65], v7 offset0:132 offset1:140
	ds_read2_b32 v[78:79], v7 offset0:165 offset1:173
	ds_read2_b32 v[80:81], v7 offset0:198 offset1:206
	ds_read2_b32 v[82:83], v7 offset0:231 offset1:239
	s_mov_b32 s13, s7
	v_or_b32_e32 v0, s2, v5
	v_lshl_add_u64 v[54:55], s[12:13], 1, v[12:13]
	v_lshlrev_b32_e32 v0, 12, v0
	v_lshl_add_u64 v[84:85], v[54:55], 0, v[0:1]
	v_or_b32_e32 v0, s2, v35
	s_waitcnt lgkmcnt(6)
	v_cvt_pk_bf16_f32 v50, v58, v56
	s_waitcnt lgkmcnt(4)
	v_cvt_pk_bf16_f32 v51, v60, v62
	s_waitcnt lgkmcnt(2)
	v_cvt_pk_bf16_f32 v52, v64, v78
	s_waitcnt lgkmcnt(0)
	v_cvt_pk_bf16_f32 v53, v80, v82
	v_lshlrev_b32_e32 v0, 12, v0
	global_store_dwordx4 v[84:85], v[50:53], off
	s_nop 1
	v_cvt_pk_bf16_f32 v50, v59, v57
	v_cvt_pk_bf16_f32 v51, v61, v63
	v_cvt_pk_bf16_f32 v52, v65, v79
	v_cvt_pk_bf16_f32 v53, v81, v83
	v_lshl_add_u64 v[56:57], v[54:55], 0, v[0:1]
	global_store_dwordx4 v[56:57], v[50:53], off
	ds_read2_b32 v[56:57], v7 offset0:49 offset1:57
	ds_read2_b32 v[58:59], v7 offset0:16 offset1:24
	ds_read2_b32 v[60:61], v7 offset0:82 offset1:90
	ds_read2_b32 v[62:63], v7 offset0:115 offset1:123
	ds_read2_b32 v[64:65], v7 offset0:148 offset1:156
	ds_read2_b32 v[78:79], v7 offset0:181 offset1:189
	ds_read2_b32 v[80:81], v7 offset0:214 offset1:222
	ds_read2_b32 v[82:83], v7 offset0:247 offset1:255
	v_or_b32_e32 v0, s2, v67
	v_lshlrev_b32_e32 v0, 12, v0
	v_lshl_add_u64 v[84:85], v[54:55], 0, v[0:1]
	v_or_b32_e32 v0, s2, v68
	s_waitcnt lgkmcnt(6)
	v_cvt_pk_bf16_f32 v50, v58, v56
	s_waitcnt lgkmcnt(4)
	v_cvt_pk_bf16_f32 v51, v60, v62
	s_waitcnt lgkmcnt(2)
	v_cvt_pk_bf16_f32 v52, v64, v78
	s_waitcnt lgkmcnt(0)
	v_cvt_pk_bf16_f32 v53, v80, v82
	v_lshlrev_b32_e32 v0, 12, v0
	global_store_dwordx4 v[84:85], v[50:53], off
	v_lshl_add_u64 v[54:55], v[54:55], 0, v[0:1]
	s_nop 0
	v_cvt_pk_bf16_f32 v50, v59, v57
	v_cvt_pk_bf16_f32 v51, v61, v63
	v_cvt_pk_bf16_f32 v52, v65, v79
	v_cvt_pk_bf16_f32 v53, v81, v83
	global_store_dwordx4 v[54:55], v[50:53], off
	s_waitcnt lgkmcnt(0)

; #define LAS __attribute__((address_space(3)))
; #define LDS_WAIT() asm volatile("s_waitcnt lgkmcnt(0)" ::: "memory")
; __device__ __forceinline__ void tr_item(const float* W, int ldw, int src_col, int nvalid, int k0, bf16_t* WT, int ldt, int dst_row, int dst_k, LAS float* scr, int lane) {
; #pragma unroll 8
;     for (int i = 0; i < 32; ++i) { const int kk = 2 * i + (lane >> 5), c = lane & 31; scr[kk * 33 + c] = (c < nvalid) ? W[(size_t)(k0 + kk) * ldw + src_col + c] : 0.f; }
;     LDS_WAIT();
.LBB0_1431:
	s_lshl_b32 s11, s13, 1
	s_lshl_b32 s10, s6, 1
	v_or_b32_e32 v49, s11, v2
	v_or_b32_e32 v0, s10, v3
	v_add_u32_e32 v54, s12, v49
	v_add_u32_e32 v52, s3, v0
	v_ashrrev_i32_e32 v55, 31, v54
	v_ashrrev_i32_e32 v53, 31, v52
	v_lshlrev_b64 v[54:55], 10, v[54:55]
	v_lshlrev_b64 v[52:53], 10, v[52:53]
	v_lshl_add_u64 v[54:55], v[50:51], 0, v[54:55]
	v_lshl_add_u64 v[52:53], v[50:51], 0, v[52:53]
	global_load_dword v132, v[54:55], off
	global_load_dword v133, v[52:53], off
	v_mad_u64_u32 v[52:53], s[18:19], v49, s53, v[6:7]
	v_mad_u64_u32 v[54:55], s[18:19], v0, s53, v[6:7]
	s_add_i32 s18, s11, 4
	s_add_i32 s17, s10, 4
	v_or_b32_e32 v49, s18, v2
	v_or_b32_e32 v0, s17, v3
	s_add_i32 s17, s10, 8
	s_add_i32 s13, s13, 16
	s_add_i32 s6, s6, 16
	s_add_i32 s16, s16, -16
	v_mov_b32_e32 v148, v52
	v_mov_b32_e32 v149, v54
	v_add_u32_e32 v54, s12, v49
	v_add_u32_e32 v52, s3, v0
	v_ashrrev_i32_e32 v55, 31, v54
	v_ashrrev_i32_e32 v53, 31, v52
	v_lshlrev_b64 v[54:55], 10, v[54:55]
	v_lshlrev_b64 v[52:53], 10, v[52:53]
	v_lshl_add_u64 v[54:55], v[50:51], 0, v[54:55]
	v_lshl_add_u64 v[52:53], v[50:51], 0, v[52:53]
	global_load_dword v134, v[54:55], off
	global_load_dword v135, v[52:53], off
	v_mad_u64_u32 v[52:53], s[18:19], v49, s53, v[6:7]
	v_mad_u64_u32 v[54:55], s[18:19], v0, s53, v[6:7]
	s_add_i32 s18, s11, 8
	s_nop 0
	v_or_b32_e32 v49, s18, v2
	v_or_b32_e32 v0, s17, v3
	s_add_i32 s17, s10, 12
	v_mov_b32_e32 v150, v52
	v_mov_b32_e32 v151, v54
	v_add_u32_e32 v54, s12, v49
	v_add_u32_e32 v52, s3, v0
	v_ashrrev_i32_e32 v55, 31, v54
	v_ashrrev_i32_e32 v53, 31, v52
	v_lshlrev_b64 v[54:55], 10, v[54:55]
	v_lshlrev_b64 v[52:53], 10, v[52:53]
	v_lshl_add_u64 v[54:55], v[50:51], 0, v[54:55]
	v_lshl_add_u64 v[52:53], v[50:51], 0, v[52:53]
	global_load_dword v136, v[54:55], off
	global_load_dword v137, v[52:53], off
	v_mad_u64_u32 v[52:53], s[18:19], v49, s53, v[6:7]
	v_mad_u64_u32 v[54:55], s[18:19], v0, s53, v[6:7]
	s_add_i32 s18, s11, 12
	s_nop 0
	v_or_b32_e32 v49, s18, v2
	v_or_b32_e32 v0, s17, v3
	s_add_i32 s17, s10, 16
	v_mov_b32_e32 v152, v52
	v_mov_b32_e32 v153, v54
	v_add_u32_e32 v54, s12, v49
	v_add_u32_e32 v52, s3, v0
	v_ashrrev_i32_e32 v55, 31, v54
	v_ashrrev_i32_e32 v53, 31, v52
	v_lshlrev_b64 v[54:55], 10, v[54:55]
	v_lshlrev_b64 v[52:53], 10, v[52:53]
	v_lshl_add_u64 v[54:55], v[50:51], 0, v[54:55]
	v_lshl_add_u64 v[52:53], v[50:51], 0, v[52:53]
	global_load_dword v138, v[54:55], off
	global_load_dword v139, v[52:53], off
	v_mad_u64_u32 v[52:53], s[18:19], v49, s53, v[6:7]
	v_mad_u64_u32 v[54:55], s[18:19], v0, s53, v[6:7]
	s_add_i32 s18, s11, 16
	s_nop 0
	v_or_b32_e32 v49, s18, v2
	v_or_b32_e32 v0, s17, v3
	s_add_i32 s17, s10, 20
	v_mov_b32_e32 v154, v52
	v_mov_b32_e32 v155, v54
	v_add_u32_e32 v54, s12, v49
	v_add_u32_e32 v52, s3, v0
	v_ashrrev_i32_e32 v55, 31, v54
	v_ashrrev_i32_e32 v53, 31, v52
	v_lshlrev_b64 v[54:55], 10, v[54:55]
	v_lshlrev_b64 v[52:53], 10, v[52:53]
	v_lshl_add_u64 v[54:55], v[50:51], 0, v[54:55]
	v_lshl_add_u64 v[52:53], v[50:51], 0, v[52:53]
	global_load_dword v140, v[54:55], off
	global_load_dword v141, v[52:53], off
	v_mad_u64_u32 v[52:53], s[18:19], v49, s53, v[6:7]
	v_mad_u64_u32 v[54:55], s[18:19], v0, s53, v[6:7]
	s_add_i32 s18, s11, 20
	s_nop 0
	v_or_b32_e32 v49, s18, v2
	v_or_b32_e32 v0, s17, v3
	s_add_i32 s17, s10, 24
	s_add_i32 s10, s10, 28
	v_mov_b32_e32 v156, v52
	v_mov_b32_e32 v157, v54
	v_add_u32_e32 v54, s12, v49
	v_add_u32_e32 v52, s3, v0
	v_ashrrev_i32_e32 v55, 31, v54
	v_ashrrev_i32_e32 v53, 31, v52
	v_lshlrev_b64 v[54:55], 10, v[54:55]
	v_lshlrev_b64 v[52:53], 10, v[52:53]
	v_lshl_add_u64 v[54:55], v[50:51], 0, v[54:55]
	v_lshl_add_u64 v[52:53], v[50:51], 0, v[52:53]
	global_load_dword v142, v[54:55], off
	global_load_dword v143, v[52:53], off
	v_mad_u64_u32 v[52:53], s[18:19], v49, s53, v[6:7]
	v_mad_u64_u32 v[54:55], s[18:19], v0, s53, v[6:7]
	s_add_i32 s18, s11, 24
	s_nop 0
	v_or_b32_e32 v49, s18, v2
	v_or_b32_e32 v0, s17, v3
	s_add_i32 s11, s11, 28
	s_cmp_lg_u32 s16, 0
	v_mov_b32_e32 v158, v52
	v_mov_b32_e32 v159, v54
	v_add_u32_e32 v54, s12, v49
	v_add_u32_e32 v52, s3, v0
	v_ashrrev_i32_e32 v55, 31, v54
	v_ashrrev_i32_e32 v53, 31, v52
	v_lshlrev_b64 v[54:55], 10, v[54:55]
	v_lshlrev_b64 v[52:53], 10, v[52:53]
	v_lshl_add_u64 v[54:55], v[50:51], 0, v[54:55]
	v_lshl_add_u64 v[52:53], v[50:51], 0, v[52:53]
	global_load_dword v144, v[54:55], off
	global_load_dword v145, v[52:53], off
	v_mad_u64_u32 v[52:53], s[18:19], v49, s53, v[6:7]
	v_mad_u64_u32 v[54:55], s[18:19], v0, s53, v[6:7]
	v_or_b32_e32 v49, s11, v2
	v_or_b32_e32 v0, s10, v3
	v_mov_b32_e32 v160, v52
	v_mov_b32_e32 v161, v54
	v_add_u32_e32 v54, s12, v49
	v_add_u32_e32 v52, s3, v0
	v_ashrrev_i32_e32 v55, 31, v54
	v_ashrrev_i32_e32 v53, 31, v52
	v_lshlrev_b64 v[54:55], 10, v[54:55]
	v_lshlrev_b64 v[52:53], 10, v[52:53]
	v_lshl_add_u64 v[54:55], v[50:51], 0, v[54:55]
	v_lshl_add_u64 v[52:53], v[50:51], 0, v[52:53]
	global_load_dword v146, v[54:55], off
	global_load_dword v147, v[52:53], off
	v_mad_u64_u32 v[52:53], s[10:11], v49, s53, v[6:7]
	v_mad_u64_u32 v[54:55], s[10:11], v0, s53, v[6:7]
	v_mov_b32_e32 v162, v52
	v_mov_b32_e32 v163, v54
	s_waitcnt vmcnt(15)
	ds_write_b32 v148, v132
	s_waitcnt vmcnt(14)
	ds_write_b32 v149, v133
	s_waitcnt vmcnt(13)
	ds_write_b32 v150, v134
	s_waitcnt vmcnt(12)
	ds_write_b32 v151, v135
	s_waitcnt vmcnt(11)
	ds_write_b32 v152, v136
	s_waitcnt vmcnt(10)
	ds_write_b32 v153, v137
	s_waitcnt vmcnt(9)
	ds_write_b32 v154, v138
	s_waitcnt vmcnt(8)
	ds_write_b32 v155, v139
	s_waitcnt vmcnt(7)
	ds_write_b32 v156, v140
	s_waitcnt vmcnt(6)
	ds_write_b32 v157, v141
	s_waitcnt vmcnt(5)
	ds_write_b32 v158, v142
	s_waitcnt vmcnt(4)
	ds_write_b32 v159, v143
	s_waitcnt vmcnt(3)
	ds_write_b32 v160, v144
	s_waitcnt vmcnt(2)
	ds_write_b32 v161, v145
	s_waitcnt vmcnt(1)
	ds_write_b32 v162, v146
	s_waitcnt vmcnt(0)
	ds_write_b32 v163, v147
	s_cbranch_scc1 .LBB0_1431
; #define LAS __attribute__((address_space(3)))
; __device__ __forceinline__ unsigned cvt_pk_bf16(float lo, float hi) { f32x2_t v = {lo, hi}; bf16x2_t b = __builtin_convertvector(v, bf16x2_t); return __builtin_bit_cast(unsigned, b); }
; #define LDS_WAIT() asm volatile("s_waitcnt lgkmcnt(0)" ::: "memory")
; __device__ __forceinline__ void tr_item(const float* W, int ldw, int src_col, int nvalid, int k0, bf16_t* WT, int ldt, int dst_row, int dst_k, LAS float* scr, int lane) {
;     ...
;     const int c = lane & 7;
; #pragma unroll
;     for (int j = 0; j < 4; ++j) { const int n = (lane >> 3) + 8 * j; const LAS float* s = scr + (8 * c) * 33 + n;
;         u32x4 o; o.x = cvt_pk_bf16(s[0 * 33], s[1 * 33]); o.y = cvt_pk_bf16(s[2 * 33], s[3 * 33]); o.z = cvt_pk_bf16(s[4 * 33], s[5 * 33]); o.w = cvt_pk_bf16(s[6 * 33], s[7 * 33]);
;         *(u32x4*)(WT + (size_t)(dst_row + n) * ldt + dst_k + k0 + 8 * c) = o; }
;     LDS_WAIT();
	s_waitcnt lgkmcnt(0)
	ds_read2_b32 v[56:57], v7 offset0:33 offset1:41
	ds_read2_b32 v[58:59], v7 offset1:8
	ds_read2_b32 v[60:61], v7 offset0:66 offset1:74
	ds_read2_b32 v[62:63], v7 offset0:99 offset1:107
	ds_read2_b32 v[64:65], v7 offset0:132 offset1:140
	ds_read2_b32 v[78:79], v7 offset0:165 offset1:173
	ds_read2_b32 v[80:81], v7 offset0:198 offset1:206
	ds_read2_b32 v[82:83], v7 offset0:231 offset1:239
	s_mov_b32 s13, s7
	v_or_b32_e32 v0, s2, v5
	v_lshl_add_u64 v[54:55], s[12:13], 1, v[14:15]
	v_lshlrev_b32_e32 v0, 12, v0
	v_lshl_add_u64 v[84:85], v[54:55], 0, v[0:1]
	v_or_b32_e32 v0, s2, v35
	s_waitcnt lgkmcnt(6)
	v_cvt_pk_bf16_f32 v50, v58, v56
	s_waitcnt lgkmcnt(4)
	v_cvt_pk_bf16_f32 v51, v60, v62
	s_waitcnt lgkmcnt(2)
	v_cvt_pk_bf16_f32 v52, v64, v78
	s_waitcnt lgkmcnt(0)
	v_cvt_pk_bf16_f32 v53, v80, v82
	v_lshlrev_b32_e32 v0, 12, v0
	global_store_dwordx4 v[84:85], v[50:53], off
	s_nop 1
	v_cvt_pk_bf16_f32 v50, v59, v57
	v_cvt_pk_bf16_f32 v51, v61, v63
	v_cvt_pk_bf16_f32 v52, v65, v79
	v_cvt_pk_bf16_f32 v53, v81, v83
	v_lshl_add_u64 v[56:57], v[54:55], 0, v[0:1]
	global_store_dwordx4 v[56:57], v[50:53], off
	ds_read2_b32 v[56:57], v7 offset0:49 offset1:57
	ds_read2_b32 v[58:59], v7 offset0:16 offset1:24
	ds_read2_b32 v[60:61], v7 offset0:82 offset1:90
	ds_read2_b32 v[62:63], v7 offset0:115 offset1:123
	ds_read2_b32 v[64:65], v7 offset0:148 offset1:156
	ds_read2_b32 v[78:79], v7 offset0:181 offset1:189
	ds_read2_b32 v[80:81], v7 offset0:214 offset1:222
	ds_read2_b32 v[82:83], v7 offset0:247 offset1:255
	v_or_b32_e32 v0, s2, v67
	v_lshlrev_b32_e32 v0, 12, v0
	v_lshl_add_u64 v[84:85], v[54:55], 0, v[0:1]
	v_or_b32_e32 v0, s2, v68
	s_waitcnt lgkmcnt(6)
	v_cvt_pk_bf16_f32 v50, v58, v56
	s_waitcnt lgkmcnt(4)
	v_cvt_pk_bf16_f32 v51, v60, v62
	s_waitcnt lgkmcnt(2)
	v_cvt_pk_bf16_f32 v52, v64, v78
	s_waitcnt lgkmcnt(0)
	v_cvt_pk_bf16_f32 v53, v80, v82
	v_lshlrev_b32_e32 v0, 12, v0
	global_store_dwordx4 v[84:85], v[50:53], off
	v_lshl_add_u64 v[54:55], v[54:55], 0, v[0:1]
	s_nop 0
	v_cvt_pk_bf16_f32 v50, v59, v57
	v_cvt_pk_bf16_f32 v51, v61, v63
	v_cvt_pk_bf16_f32 v52, v65, v79
	v_cvt_pk_bf16_f32 v53, v81, v83
	global_store_dwordx4 v[54:55], v[50:53], off
	s_waitcnt lgkmcnt(0)

; #define LAS __attribute__((address_space(3)))
; #define LDS_WAIT() asm volatile("s_waitcnt lgkmcnt(0)" ::: "memory")
; __device__ __forceinline__ void tr_item(const float* W, int ldw, int src_col, int nvalid, int k0, bf16_t* WT, int ldt, int dst_row, int dst_k, LAS float* scr, int lane) {
; #pragma unroll 8
;     for (int i = 0; i < 32; ++i) { const int kk = 2 * i + (lane >> 5), c = lane & 31; scr[kk * 33 + c] = (c < nvalid) ? W[(size_t)(k0 + kk) * ldw + src_col + c] : 0.f; }
;     LDS_WAIT();
.LBB0_1436:
	s_lshl_b32 s11, s13, 1
	s_lshl_b32 s10, s3, 1
	v_or_b32_e32 v49, s11, v2
	v_or_b32_e32 v0, s10, v3
	v_add_u32_e32 v54, s12, v49
	v_add_u32_e32 v52, s6, v0
	v_ashrrev_i32_e32 v55, 31, v54
	v_ashrrev_i32_e32 v53, 31, v52
	v_lshlrev_b64 v[54:55], 12, v[54:55]
	v_lshlrev_b64 v[52:53], 12, v[52:53]
	v_lshl_add_u64 v[54:55], v[50:51], 0, v[54:55]
	v_lshl_add_u64 v[52:53], v[50:51], 0, v[52:53]
	global_load_dword v132, v[54:55], off
	global_load_dword v133, v[52:53], off
	v_mad_u64_u32 v[52:53], s[18:19], v49, s53, v[6:7]
	v_mad_u64_u32 v[54:55], s[18:19], v0, s53, v[6:7]
	s_add_i32 s18, s11, 4
	s_add_i32 s17, s10, 4
	v_or_b32_e32 v49, s18, v2
	v_or_b32_e32 v0, s17, v3
	s_add_i32 s17, s10, 8
	s_add_i32 s13, s13, 16
	s_add_i32 s3, s3, 16
	s_add_i32 s16, s16, -16
	v_mov_b32_e32 v148, v52
	v_mov_b32_e32 v149, v54
	v_add_u32_e32 v54, s12, v49
	v_add_u32_e32 v52, s6, v0
	v_ashrrev_i32_e32 v55, 31, v54
	v_ashrrev_i32_e32 v53, 31, v52
	v_lshlrev_b64 v[54:55], 12, v[54:55]
	v_lshlrev_b64 v[52:53], 12, v[52:53]
	v_lshl_add_u64 v[54:55], v[50:51], 0, v[54:55]
	v_lshl_add_u64 v[52:53], v[50:51], 0, v[52:53]
	global_load_dword v134, v[54:55], off
	global_load_dword v135, v[52:53], off
	v_mad_u64_u32 v[52:53], s[18:19], v49, s53, v[6:7]
	v_mad_u64_u32 v[54:55], s[18:19], v0, s53, v[6:7]
	s_add_i32 s18, s11, 8
	s_nop 0
	v_or_b32_e32 v49, s18, v2
	v_or_b32_e32 v0, s17, v3
	s_add_i32 s17, s10, 12
	v_mov_b32_e32 v150, v52
	v_mov_b32_e32 v151, v54
	v_add_u32_e32 v54, s12, v49
	v_add_u32_e32 v52, s6, v0
	v_ashrrev_i32_e32 v55, 31, v54
	v_ashrrev_i32_e32 v53, 31, v52
	v_lshlrev_b64 v[54:55], 12, v[54:55]
	v_lshlrev_b64 v[52:53], 12, v[52:53]
	v_lshl_add_u64 v[54:55], v[50:51], 0, v[54:55]
	v_lshl_add_u64 v[52:53], v[50:51], 0, v[52:53]
	global_load_dword v136, v[54:55], off
	global_load_dword v137, v[52:53], off
	v_mad_u64_u32 v[52:53], s[18:19], v49, s53, v[6:7]
	v_mad_u64_u32 v[54:55], s[18:19], v0, s53, v[6:7]
	s_add_i32 s18, s11, 12
	s_nop 0
	v_or_b32_e32 v49, s18, v2
	v_or_b32_e32 v0, s17, v3
	s_add_i32 s17, s10, 16
	v_mov_b32_e32 v152, v52
	v_mov_b32_e32 v153, v54
	v_add_u32_e32 v54, s12, v49
	v_add_u32_e32 v52, s6, v0
	v_ashrrev_i32_e32 v55, 31, v54
	v_ashrrev_i32_e32 v53, 31, v52
	v_lshlrev_b64 v[54:55], 12, v[54:55]
	v_lshlrev_b64 v[52:53], 12, v[52:53]
	v_lshl_add_u64 v[54:55], v[50:51], 0, v[54:55]
	v_lshl_add_u64 v[52:53], v[50:51], 0, v[52:53]
	global_load_dword v138, v[54:55], off
	global_load_dword v139, v[52:53], off
	v_mad_u64_u32 v[52:53], s[18:19], v49, s53, v[6:7]
	v_mad_u64_u32 v[54:55], s[18:19], v0, s53, v[6:7]
	s_add_i32 s18, s11, 16
	s_nop 0
	v_or_b32_e32 v49, s18, v2
	v_or_b32_e32 v0, s17, v3
	s_add_i32 s17, s10, 20
	v_mov_b32_e32 v154, v52
	v_mov_b32_e32 v155, v54
	v_add_u32_e32 v54, s12, v49
	v_add_u32_e32 v52, s6, v0
	v_ashrrev_i32_e32 v55, 31, v54
	v_ashrrev_i32_e32 v53, 31, v52
	v_lshlrev_b64 v[54:55], 12, v[54:55]
	v_lshlrev_b64 v[52:53], 12, v[52:53]
	v_lshl_add_u64 v[54:55], v[50:51], 0, v[54:55]
	v_lshl_add_u64 v[52:53], v[50:51], 0, v[52:53]
	global_load_dword v140, v[54:55], off
	global_load_dword v141, v[52:53], off
	v_mad_u64_u32 v[52:53], s[18:19], v49, s53, v[6:7]
	v_mad_u64_u32 v[54:55], s[18:19], v0, s53, v[6:7]
	s_add_i32 s18, s11, 20
	s_nop 0
	v_or_b32_e32 v49, s18, v2
	v_or_b32_e32 v0, s17, v3
	s_add_i32 s17, s10, 24
	s_add_i32 s10, s10, 28
	v_mov_b32_e32 v156, v52
	v_mov_b32_e32 v157, v54
	v_add_u32_e32 v54, s12, v49
	v_add_u32_e32 v52, s6, v0
	v_ashrrev_i32_e32 v55, 31, v54
	v_ashrrev_i32_e32 v53, 31, v52
	v_lshlrev_b64 v[54:55], 12, v[54:55]
	v_lshlrev_b64 v[52:53], 12, v[52:53]
	v_lshl_add_u64 v[54:55], v[50:51], 0, v[54:55]
	v_lshl_add_u64 v[52:53], v[50:51], 0, v[52:53]
	global_load_dword v142, v[54:55], off
	global_load_dword v143, v[52:53], off
	v_mad_u64_u32 v[52:53], s[18:19], v49, s53, v[6:7]
	v_mad_u64_u32 v[54:55], s[18:19], v0, s53, v[6:7]
	s_add_i32 s18, s11, 24
	s_nop 0
	v_or_b32_e32 v49, s18, v2
	v_or_b32_e32 v0, s17, v3
	s_add_i32 s11, s11, 28
	s_cmp_lg_u32 s16, 0
	v_mov_b32_e32 v158, v52
	v_mov_b32_e32 v159, v54
	v_add_u32_e32 v54, s12, v49
	v_add_u32_e32 v52, s6, v0
	v_ashrrev_i32_e32 v55, 31, v54
	v_ashrrev_i32_e32 v53, 31, v52
	v_lshlrev_b64 v[54:55], 12, v[54:55]
	v_lshlrev_b64 v[52:53], 12, v[52:53]
	v_lshl_add_u64 v[54:55], v[50:51], 0, v[54:55]
	v_lshl_add_u64 v[52:53], v[50:51], 0, v[52:53]
	global_load_dword v144, v[54:55], off
	global_load_dword v145, v[52:53], off
	v_mad_u64_u32 v[52:53], s[18:19], v49, s53, v[6:7]
	v_mad_u64_u32 v[54:55], s[18:19], v0, s53, v[6:7]
	v_or_b32_e32 v49, s11, v2
	v_or_b32_e32 v0, s10, v3
	v_mov_b32_e32 v160, v52
	v_mov_b32_e32 v161, v54
	v_add_u32_e32 v54, s12, v49
	v_add_u32_e32 v52, s6, v0
	v_ashrrev_i32_e32 v55, 31, v54
	v_ashrrev_i32_e32 v53, 31, v52
	v_lshlrev_b64 v[54:55], 12, v[54:55]
	v_lshlrev_b64 v[52:53], 12, v[52:53]
	v_lshl_add_u64 v[54:55], v[50:51], 0, v[54:55]
	v_lshl_add_u64 v[52:53], v[50:51], 0, v[52:53]
	global_load_dword v146, v[54:55], off
	global_load_dword v147, v[52:53], off
	v_mad_u64_u32 v[52:53], s[10:11], v49, s53, v[6:7]
	v_mad_u64_u32 v[54:55], s[10:11], v0, s53, v[6:7]
	v_mov_b32_e32 v162, v52
	v_mov_b32_e32 v163, v54
	s_waitcnt vmcnt(15)
	ds_write_b32 v148, v132
	s_waitcnt vmcnt(14)
	ds_write_b32 v149, v133
	s_waitcnt vmcnt(13)
	ds_write_b32 v150, v134
	s_waitcnt vmcnt(12)
	ds_write_b32 v151, v135
	s_waitcnt vmcnt(11)
	ds_write_b32 v152, v136
	s_waitcnt vmcnt(10)
	ds_write_b32 v153, v137
	s_waitcnt vmcnt(9)
	ds_write_b32 v154, v138
	s_waitcnt vmcnt(8)
	ds_write_b32 v155, v139
	s_waitcnt vmcnt(7)
	ds_write_b32 v156, v140
	s_waitcnt vmcnt(6)
	ds_write_b32 v157, v141
	s_waitcnt vmcnt(5)
	ds_write_b32 v158, v142
	s_waitcnt vmcnt(4)
	ds_write_b32 v159, v143
	s_waitcnt vmcnt(3)
	ds_write_b32 v160, v144
	s_waitcnt vmcnt(2)
	ds_write_b32 v161, v145
	s_waitcnt vmcnt(1)
	ds_write_b32 v162, v146
	s_waitcnt vmcnt(0)
	ds_write_b32 v163, v147
	s_cbranch_scc1 .LBB0_1436
; #define LAS __attribute__((address_space(3)))
; __device__ __forceinline__ unsigned cvt_pk_bf16(float lo, float hi) { f32x2_t v = {lo, hi}; bf16x2_t b = __builtin_convertvector(v, bf16x2_t); return __builtin_bit_cast(unsigned, b); }
; #define LDS_WAIT() asm volatile("s_waitcnt lgkmcnt(0)" ::: "memory")
; __device__ __forceinline__ void tr_item(const float* W, int ldw, int src_col, int nvalid, int k0, bf16_t* WT, int ldt, int dst_row, int dst_k, LAS float* scr, int lane) {
;     ...
;     const int c = lane & 7;
; #pragma unroll
;     for (int j = 0; j < 4; ++j) { const int n = (lane >> 3) + 8 * j; const LAS float* s = scr + (8 * c) * 33 + n;
;         u32x4 o; o.x = cvt_pk_bf16(s[0 * 33], s[1 * 33]); o.y = cvt_pk_bf16(s[2 * 33], s[3 * 33]); o.z = cvt_pk_bf16(s[4 * 33], s[5 * 33]); o.w = cvt_pk_bf16(s[6 * 33], s[7 * 33]);
;         *(u32x4*)(WT + (size_t)(dst_row + n) * ldt + dst_k + k0 + 8 * c) = o; }
;     LDS_WAIT();
	s_waitcnt lgkmcnt(0)
	ds_read2_b32 v[56:57], v7 offset0:33 offset1:41
	ds_read2_b32 v[58:59], v7 offset1:8
	ds_read2_b32 v[60:61], v7 offset0:66 offset1:74
	ds_read2_b32 v[62:63], v7 offset0:99 offset1:107
	ds_read2_b32 v[64:65], v7 offset0:132 offset1:140
	ds_read2_b32 v[78:79], v7 offset0:165 offset1:173
	ds_read2_b32 v[80:81], v7 offset0:198 offset1:206
	ds_read2_b32 v[82:83], v7 offset0:231 offset1:239
	s_mov_b32 s13, s7
	v_or_b32_e32 v0, s2, v5
	v_lshl_add_u64 v[54:55], s[12:13], 1, v[16:17]
	v_mul_u32_u24_e32 v0, 0x1600, v0
	v_lshl_add_u64 v[84:85], v[54:55], 0, v[0:1]
	v_or_b32_e32 v0, s2, v35
	s_waitcnt lgkmcnt(6)
	v_cvt_pk_bf16_f32 v50, v58, v56
	s_waitcnt lgkmcnt(4)
	v_cvt_pk_bf16_f32 v51, v60, v62
	s_waitcnt lgkmcnt(2)
	v_cvt_pk_bf16_f32 v52, v64, v78
	s_waitcnt lgkmcnt(0)
	v_cvt_pk_bf16_f32 v53, v80, v82
	v_mul_u32_u24_e32 v0, 0x1600, v0
	global_store_dwordx4 v[84:85], v[50:53], off
	s_nop 1
	v_cvt_pk_bf16_f32 v50, v59, v57
	v_cvt_pk_bf16_f32 v51, v61, v63
	v_cvt_pk_bf16_f32 v52, v65, v79
	v_cvt_pk_bf16_f32 v53, v81, v83
	v_lshl_add_u64 v[56:57], v[54:55], 0, v[0:1]
	global_store_dwordx4 v[56:57], v[50:53], off
	ds_read2_b32 v[56:57], v7 offset0:16 offset1:24
	ds_read2_b32 v[58:59], v7 offset0:49 offset1:57
	ds_read2_b32 v[60:61], v7 offset0:82 offset1:90
	ds_read2_b32 v[62:63], v7 offset0:115 offset1:123
	ds_read2_b32 v[64:65], v7 offset0:148 offset1:156
	ds_read2_b32 v[78:79], v7 offset0:181 offset1:189
	ds_read2_b32 v[80:81], v7 offset0:214 offset1:222
	ds_read2_b32 v[82:83], v7 offset0:247 offset1:255
	v_or_b32_e32 v0, s2, v67
	v_mul_u32_u24_e32 v0, 0x1600, v0
	v_lshl_add_u64 v[84:85], v[54:55], 0, v[0:1]
	v_or_b32_e32 v0, s2, v68
	s_waitcnt lgkmcnt(6)
	v_cvt_pk_bf16_f32 v50, v56, v58
	s_waitcnt lgkmcnt(4)
	v_cvt_pk_bf16_f32 v51, v60, v62
	s_waitcnt lgkmcnt(2)
	v_cvt_pk_bf16_f32 v52, v64, v78
	s_waitcnt lgkmcnt(0)
	v_cvt_pk_bf16_f32 v53, v80, v82
	v_mul_u32_u24_e32 v0, 0x1600, v0
	global_store_dwordx4 v[84:85], v[50:53], off
	v_lshl_add_u64 v[54:55], v[54:55], 0, v[0:1]
	s_nop 0
	v_cvt_pk_bf16_f32 v50, v57, v59
	v_cvt_pk_bf16_f32 v51, v61, v63
	v_cvt_pk_bf16_f32 v52, v65, v79
	v_cvt_pk_bf16_f32 v53, v81, v83
	global_store_dwordx4 v[54:55], v[50:53], off
	s_waitcnt lgkmcnt(0)

; #define LAS __attribute__((address_space(3)))
; #define LDS_WAIT() asm volatile("s_waitcnt lgkmcnt(0)" ::: "memory")
; __device__ __forceinline__ void tr_item(const float* W, int ldw, int src_col, int nvalid, int k0, bf16_t* WT, int ldt, int dst_row, int dst_k, LAS float* scr, int lane) {
; #pragma unroll 8
;     for (int i = 0; i < 32; ++i) { const int kk = 2 * i + (lane >> 5), c = lane & 31; scr[kk * 33 + c] = (c < nvalid) ? W[(size_t)(k0 + kk) * ldw + src_col + c] : 0.f; }
;     LDS_WAIT();
.LBB0_1441:
	s_lshl_b32 s16, s11, 1
	s_lshl_b32 s13, s10, 1
	v_or_b32_e32 v49, s16, v2
	v_or_b32_e32 v0, s13, v3
	v_add_u32_e32 v52, s3, v49
	v_add_u32_e32 v54, s6, v0
	v_mad_u64_u32 v[52:53], s[18:19], v52, s54, v[50:51]
	v_mad_u64_u32 v[54:55], s[18:19], v54, s54, v[50:51]
	global_load_dword v132, v[52:53], off
	global_load_dword v133, v[54:55], off
	v_mad_u64_u32 v[52:53], s[18:19], v49, s53, v[6:7]
	v_mad_u64_u32 v[54:55], s[18:19], v0, s53, v[6:7]
	s_add_i32 s18, s16, 4
	s_add_i32 s17, s13, 4
	v_or_b32_e32 v49, s18, v2
	v_or_b32_e32 v0, s17, v3
	s_add_i32 s17, s13, 8
	s_add_i32 s11, s11, 16
	s_add_i32 s10, s10, 16
	s_add_i32 s12, s12, -16
	v_mov_b32_e32 v148, v52
	v_mov_b32_e32 v149, v54
	v_add_u32_e32 v52, s3, v49
	v_add_u32_e32 v54, s6, v0
	v_mad_u64_u32 v[52:53], s[18:19], v52, s54, v[50:51]
	v_mad_u64_u32 v[54:55], s[18:19], v54, s54, v[50:51]
	global_load_dword v134, v[52:53], off
	global_load_dword v135, v[54:55], off
	v_mad_u64_u32 v[52:53], s[18:19], v49, s53, v[6:7]
	v_mad_u64_u32 v[54:55], s[18:19], v0, s53, v[6:7]
	s_add_i32 s18, s16, 8
	s_nop 0
	v_or_b32_e32 v49, s18, v2
	v_or_b32_e32 v0, s17, v3
	s_add_i32 s17, s13, 12
	v_mov_b32_e32 v150, v52
	v_mov_b32_e32 v151, v54
	v_add_u32_e32 v52, s3, v49
	v_add_u32_e32 v54, s6, v0
	v_mad_u64_u32 v[52:53], s[18:19], v52, s54, v[50:51]
	v_mad_u64_u32 v[54:55], s[18:19], v54, s54, v[50:51]
	global_load_dword v136, v[52:53], off
	global_load_dword v137, v[54:55], off
	v_mad_u64_u32 v[52:53], s[18:19], v49, s53, v[6:7]
	v_mad_u64_u32 v[54:55], s[18:19], v0, s53, v[6:7]
	s_add_i32 s18, s16, 12
	s_nop 0
	v_or_b32_e32 v49, s18, v2
	v_or_b32_e32 v0, s17, v3
	s_add_i32 s17, s13, 16
	v_mov_b32_e32 v152, v52
	v_mov_b32_e32 v153, v54
	v_add_u32_e32 v52, s3, v49
	v_add_u32_e32 v54, s6, v0
	v_mad_u64_u32 v[52:53], s[18:19], v52, s54, v[50:51]
	v_mad_u64_u32 v[54:55], s[18:19], v54, s54, v[50:51]
	global_load_dword v138, v[52:53], off
	global_load_dword v139, v[54:55], off
	v_mad_u64_u32 v[52:53], s[18:19], v49, s53, v[6:7]
	v_mad_u64_u32 v[54:55], s[18:19], v0, s53, v[6:7]
	s_add_i32 s18, s16, 16
	s_nop 0
	v_or_b32_e32 v49, s18, v2
	v_or_b32_e32 v0, s17, v3
	s_add_i32 s17, s13, 20
	v_mov_b32_e32 v154, v52
	v_mov_b32_e32 v155, v54
	v_add_u32_e32 v52, s3, v49
	v_add_u32_e32 v54, s6, v0
	v_mad_u64_u32 v[52:53], s[18:19], v52, s54, v[50:51]
	v_mad_u64_u32 v[54:55], s[18:19], v54, s54, v[50:51]
	global_load_dword v140, v[52:53], off
	global_load_dword v141, v[54:55], off
	v_mad_u64_u32 v[52:53], s[18:19], v49, s53, v[6:7]
	v_mad_u64_u32 v[54:55], s[18:19], v0, s53, v[6:7]
	s_add_i32 s18, s16, 20
	s_nop 0
	v_or_b32_e32 v49, s18, v2
	v_or_b32_e32 v0, s17, v3
	s_add_i32 s17, s13, 24
	s_add_i32 s13, s13, 28
	v_mov_b32_e32 v156, v52
	v_mov_b32_e32 v157, v54
	v_add_u32_e32 v52, s3, v49
	v_add_u32_e32 v54, s6, v0
	v_mad_u64_u32 v[52:53], s[18:19], v52, s54, v[50:51]
	v_mad_u64_u32 v[54:55], s[18:19], v54, s54, v[50:51]
	global_load_dword v142, v[52:53], off
	global_load_dword v143, v[54:55], off
	v_mad_u64_u32 v[52:53], s[18:19], v49, s53, v[6:7]
	v_mad_u64_u32 v[54:55], s[18:19], v0, s53, v[6:7]
	s_add_i32 s18, s16, 24
	s_nop 0
	v_or_b32_e32 v49, s18, v2
	v_or_b32_e32 v0, s17, v3
	s_add_i32 s16, s16, 28
	s_cmp_lg_u32 s12, 0
	v_mov_b32_e32 v158, v52
	v_mov_b32_e32 v159, v54
	v_add_u32_e32 v52, s3, v49
	v_add_u32_e32 v54, s6, v0
	v_mad_u64_u32 v[52:53], s[18:19], v52, s54, v[50:51]
	v_mad_u64_u32 v[54:55], s[18:19], v54, s54, v[50:51]
	global_load_dword v144, v[52:53], off
	global_load_dword v145, v[54:55], off
	v_mad_u64_u32 v[52:53], s[18:19], v49, s53, v[6:7]
	v_or_b32_e32 v49, s16, v2
	v_mad_u64_u32 v[54:55], s[18:19], v0, s53, v[6:7]
	v_or_b32_e32 v0, s13, v3
	v_mov_b32_e32 v160, v52
	v_mov_b32_e32 v161, v54
	v_add_u32_e32 v52, s3, v49
	v_add_u32_e32 v54, s6, v0
	v_mad_u64_u32 v[52:53], s[16:17], v52, s54, v[50:51]
	v_mad_u64_u32 v[54:55], s[16:17], v54, s54, v[50:51]
	global_load_dword v146, v[52:53], off
	global_load_dword v147, v[54:55], off
	v_mad_u64_u32 v[52:53], s[16:17], v49, s53, v[6:7]
	v_mad_u64_u32 v[54:55], s[16:17], v0, s53, v[6:7]
	v_mov_b32_e32 v162, v52
	v_mov_b32_e32 v163, v54
	s_waitcnt vmcnt(15)
	ds_write_b32 v148, v132
	s_waitcnt vmcnt(14)
	ds_write_b32 v149, v133
	s_waitcnt vmcnt(13)
	ds_write_b32 v150, v134
	s_waitcnt vmcnt(12)
	ds_write_b32 v151, v135
	s_waitcnt vmcnt(11)
	ds_write_b32 v152, v136
	s_waitcnt vmcnt(10)
	ds_write_b32 v153, v137
	s_waitcnt vmcnt(9)
	ds_write_b32 v154, v138
	s_waitcnt vmcnt(8)
	ds_write_b32 v155, v139
	s_waitcnt vmcnt(7)
	ds_write_b32 v156, v140
	s_waitcnt vmcnt(6)
	ds_write_b32 v157, v141
	s_waitcnt vmcnt(5)
	ds_write_b32 v158, v142
	s_waitcnt vmcnt(4)
	ds_write_b32 v159, v143
	s_waitcnt vmcnt(3)
	ds_write_b32 v160, v144
	s_waitcnt vmcnt(2)
	ds_write_b32 v161, v145
	s_waitcnt vmcnt(1)
	ds_write_b32 v162, v146
	s_waitcnt vmcnt(0)
	ds_write_b32 v163, v147
	s_cbranch_scc1 .LBB0_1441
; #define LAS __attribute__((address_space(3)))
; __device__ __forceinline__ unsigned cvt_pk_bf16(float lo, float hi) { f32x2_t v = {lo, hi}; bf16x2_t b = __builtin_convertvector(v, bf16x2_t); return __builtin_bit_cast(unsigned, b); }
; #define LDS_WAIT() asm volatile("s_waitcnt lgkmcnt(0)" ::: "memory")
; __device__ __forceinline__ void tr_item(const float* W, int ldw, int src_col, int nvalid, int k0, bf16_t* WT, int ldt, int dst_row, int dst_k, LAS float* scr, int lane) {
;     ...
;     LDS_WAIT();
;     const int c = lane & 7;
; #pragma unroll
;     for (int j = 0; j < 4; ++j) { const int n = (lane >> 3) + 8 * j; const LAS float* s = scr + (8 * c) * 33 + n;
;         u32x4 o; o.x = cvt_pk_bf16(s[0 * 33], s[1 * 33]); o.y = cvt_pk_bf16(s[2 * 33], s[3 * 33]); o.z = cvt_pk_bf16(s[4 * 33], s[5 * 33]); o.w = cvt_pk_bf16(s[6 * 33], s[7 * 33]);
;         *(u32x4*)(WT + (size_t)(dst_row + n) * ldt + dst_k + k0 + 8 * c) = o; }
;     LDS_WAIT();
	s_waitcnt lgkmcnt(0)
	ds_read2_b32 v[56:57], v7 offset0:33 offset1:41
	ds_read2_b32 v[58:59], v7 offset1:8
	ds_read2_b32 v[60:61], v7 offset0:66 offset1:74
	ds_read2_b32 v[62:63], v7 offset0:99 offset1:107
	ds_read2_b32 v[64:65], v7 offset0:132 offset1:140
	ds_read2_b32 v[78:79], v7 offset0:165 offset1:173
	ds_read2_b32 v[80:81], v7 offset0:198 offset1:206
	ds_read2_b32 v[82:83], v7 offset0:231 offset1:239
	s_and_b32 s3, 0xffff, s3
	s_lshl_b32 s6, s3, 1
	v_or_b32_e32 v0, s2, v5
	v_lshl_add_u64 v[54:55], v[18:19], 0, s[6:7]
	v_lshlrev_b32_e32 v0, 11, v0
	v_lshl_add_u64 v[84:85], v[54:55], 0, v[0:1]
	v_or_b32_e32 v0, s2, v35
	s_waitcnt lgkmcnt(6)
	v_cvt_pk_bf16_f32 v50, v58, v56
	s_waitcnt lgkmcnt(4)
	v_cvt_pk_bf16_f32 v51, v60, v62
	s_waitcnt lgkmcnt(2)
	v_cvt_pk_bf16_f32 v52, v64, v78
	s_waitcnt lgkmcnt(0)
	v_cvt_pk_bf16_f32 v53, v80, v82
	v_lshlrev_b32_e32 v0, 11, v0
	global_store_dwordx4 v[84:85], v[50:53], off
	s_nop 1
	v_cvt_pk_bf16_f32 v50, v59, v57
	v_cvt_pk_bf16_f32 v51, v61, v63
	v_cvt_pk_bf16_f32 v52, v65, v79
	v_cvt_pk_bf16_f32 v53, v81, v83
	v_lshl_add_u64 v[56:57], v[54:55], 0, v[0:1]
	global_store_dwordx4 v[56:57], v[50:53], off
	ds_read2_b32 v[56:57], v7 offset0:49 offset1:57
	ds_read2_b32 v[58:59], v7 offset0:16 offset1:24
	ds_read2_b32 v[60:61], v7 offset0:82 offset1:90
	ds_read2_b32 v[62:63], v7 offset0:115 offset1:123
	ds_read2_b32 v[64:65], v7 offset0:148 offset1:156
	ds_read2_b32 v[78:79], v7 offset0:181 offset1:189
	ds_read2_b32 v[80:81], v7 offset0:214 offset1:222
	ds_read2_b32 v[82:83], v7 offset0:247 offset1:255
	v_or_b32_e32 v0, s2, v67
	v_lshlrev_b32_e32 v0, 11, v0
	v_lshl_add_u64 v[84:85], v[54:55], 0, v[0:1]
	v_or_b32_e32 v0, s2, v68
	s_waitcnt lgkmcnt(6)
	v_cvt_pk_bf16_f32 v50, v58, v56
	s_waitcnt lgkmcnt(4)
	v_cvt_pk_bf16_f32 v51, v60, v62
	s_waitcnt lgkmcnt(2)
	v_cvt_pk_bf16_f32 v52, v64, v78
	s_waitcnt lgkmcnt(0)
	v_cvt_pk_bf16_f32 v53, v80, v82
	v_lshlrev_b32_e32 v0, 11, v0
	global_store_dwordx4 v[84:85], v[50:53], off
	v_lshl_add_u64 v[54:55], v[54:55], 0, v[0:1]
	s_nop 0
	v_cvt_pk_bf16_f32 v50, v59, v57
	v_cvt_pk_bf16_f32 v51, v61, v63
	v_cvt_pk_bf16_f32 v52, v65, v79
	v_cvt_pk_bf16_f32 v53, v81, v83
	global_store_dwordx4 v[54:55], v[50:53], off
	s_waitcnt lgkmcnt(0)

; #define LAS __attribute__((address_space(3)))
; #define LDS_WAIT() asm volatile("s_waitcnt lgkmcnt(0)" ::: "memory")
; __device__ __forceinline__ void tr_item(const float* W, int ldw, int src_col, int nvalid, int k0, bf16_t* WT, int ldt, int dst_row, int dst_k, LAS float* scr, int lane) {
; #pragma unroll 8
;     for (int i = 0; i < 32; ++i) { const int kk = 2 * i + (lane >> 5), c = lane & 31; scr[kk * 33 + c] = (c < nvalid) ? W[(size_t)(k0 + kk) * ldw + src_col + c] : 0.f; }
;     LDS_WAIT();
.LBB0_1446:
	s_lshl_b32 s11, s13, 1
	s_lshl_b32 s10, s3, 1
	v_or_b32_e32 v49, s11, v2
	v_or_b32_e32 v0, s10, v3
	v_add_u32_e32 v54, s12, v49
	v_add_u32_e32 v52, s6, v0
	v_ashrrev_i32_e32 v55, 31, v54
	v_ashrrev_i32_e32 v53, 31, v52
	v_lshlrev_b64 v[54:55], 12, v[54:55]
	v_lshlrev_b64 v[52:53], 12, v[52:53]
	v_lshl_add_u64 v[54:55], v[50:51], 0, v[54:55]
	v_lshl_add_u64 v[52:53], v[50:51], 0, v[52:53]
	global_load_dword v132, v[54:55], off
	global_load_dword v133, v[52:53], off
	v_mad_u64_u32 v[52:53], s[18:19], v49, s53, v[6:7]
	v_mad_u64_u32 v[54:55], s[18:19], v0, s53, v[6:7]
	s_add_i32 s18, s11, 4
	s_add_i32 s17, s10, 4
	v_or_b32_e32 v49, s18, v2
	v_or_b32_e32 v0, s17, v3
	s_add_i32 s17, s10, 8
	s_add_i32 s13, s13, 16
	s_add_i32 s3, s3, 16
	s_add_i32 s16, s16, -16
	v_mov_b32_e32 v148, v52
	v_mov_b32_e32 v149, v54
	v_add_u32_e32 v54, s12, v49
	v_add_u32_e32 v52, s6, v0
	v_ashrrev_i32_e32 v55, 31, v54
	v_ashrrev_i32_e32 v53, 31, v52
	v_lshlrev_b64 v[54:55], 12, v[54:55]
	v_lshlrev_b64 v[52:53], 12, v[52:53]
	v_lshl_add_u64 v[54:55], v[50:51], 0, v[54:55]
	v_lshl_add_u64 v[52:53], v[50:51], 0, v[52:53]
	global_load_dword v134, v[54:55], off
	global_load_dword v135, v[52:53], off
	v_mad_u64_u32 v[52:53], s[18:19], v49, s53, v[6:7]
	v_mad_u64_u32 v[54:55], s[18:19], v0, s53, v[6:7]
	s_add_i32 s18, s11, 8
	s_nop 0
	v_or_b32_e32 v49, s18, v2
	v_or_b32_e32 v0, s17, v3
	s_add_i32 s17, s10, 12
	v_mov_b32_e32 v150, v52
	v_mov_b32_e32 v151, v54
	v_add_u32_e32 v54, s12, v49
	v_add_u32_e32 v52, s6, v0
	v_ashrrev_i32_e32 v55, 31, v54
	v_ashrrev_i32_e32 v53, 31, v52
	v_lshlrev_b64 v[54:55], 12, v[54:55]
	v_lshlrev_b64 v[52:53], 12, v[52:53]
	v_lshl_add_u64 v[54:55], v[50:51], 0, v[54:55]
	v_lshl_add_u64 v[52:53], v[50:51], 0, v[52:53]
	global_load_dword v136, v[54:55], off
	global_load_dword v137, v[52:53], off
	v_mad_u64_u32 v[52:53], s[18:19], v49, s53, v[6:7]
	v_mad_u64_u32 v[54:55], s[18:19], v0, s53, v[6:7]
	s_add_i32 s18, s11, 12
	s_nop 0
	v_or_b32_e32 v49, s18, v2
	v_or_b32_e32 v0, s17, v3
	s_add_i32 s17, s10, 16
	v_mov_b32_e32 v152, v52
	v_mov_b32_e32 v153, v54
	v_add_u32_e32 v54, s12, v49
	v_add_u32_e32 v52, s6, v0
	v_ashrrev_i32_e32 v55, 31, v54
	v_ashrrev_i32_e32 v53, 31, v52
	v_lshlrev_b64 v[54:55], 12, v[54:55]
	v_lshlrev_b64 v[52:53], 12, v[52:53]
	v_lshl_add_u64 v[54:55], v[50:51], 0, v[54:55]
	v_lshl_add_u64 v[52:53], v[50:51], 0, v[52:53]
	global_load_dword v138, v[54:55], off
	global_load_dword v139, v[52:53], off
	v_mad_u64_u32 v[52:53], s[18:19], v49, s53, v[6:7]
	v_mad_u64_u32 v[54:55], s[18:19], v0, s53, v[6:7]
	s_add_i32 s18, s11, 16
	s_nop 0
	v_or_b32_e32 v49, s18, v2
	v_or_b32_e32 v0, s17, v3
	s_add_i32 s17, s10, 20
	v_mov_b32_e32 v154, v52
	v_mov_b32_e32 v155, v54
	v_add_u32_e32 v54, s12, v49
	v_add_u32_e32 v52, s6, v0
	v_ashrrev_i32_e32 v55, 31, v54
	v_ashrrev_i32_e32 v53, 31, v52
	v_lshlrev_b64 v[54:55], 12, v[54:55]
	v_lshlrev_b64 v[52:53], 12, v[52:53]
	v_lshl_add_u64 v[54:55], v[50:51], 0, v[54:55]
	v_lshl_add_u64 v[52:53], v[50:51], 0, v[52:53]
	global_load_dword v140, v[54:55], off
	global_load_dword v141, v[52:53], off
	v_mad_u64_u32 v[52:53], s[18:19], v49, s53, v[6:7]
	v_mad_u64_u32 v[54:55], s[18:19], v0, s53, v[6:7]
	s_add_i32 s18, s11, 20
	s_nop 0
	v_or_b32_e32 v49, s18, v2
	v_or_b32_e32 v0, s17, v3
	s_add_i32 s17, s10, 24
	s_add_i32 s10, s10, 28
	v_mov_b32_e32 v156, v52
	v_mov_b32_e32 v157, v54
	v_add_u32_e32 v54, s12, v49
	v_add_u32_e32 v52, s6, v0
	v_ashrrev_i32_e32 v55, 31, v54
	v_ashrrev_i32_e32 v53, 31, v52
	v_lshlrev_b64 v[54:55], 12, v[54:55]
	v_lshlrev_b64 v[52:53], 12, v[52:53]
	v_lshl_add_u64 v[54:55], v[50:51], 0, v[54:55]
	v_lshl_add_u64 v[52:53], v[50:51], 0, v[52:53]
	global_load_dword v142, v[54:55], off
	global_load_dword v143, v[52:53], off
	v_mad_u64_u32 v[52:53], s[18:19], v49, s53, v[6:7]
	v_mad_u64_u32 v[54:55], s[18:19], v0, s53, v[6:7]
	s_add_i32 s18, s11, 24
	s_nop 0
	v_or_b32_e32 v49, s18, v2
	v_or_b32_e32 v0, s17, v3
	s_add_i32 s11, s11, 28
	s_cmp_lg_u32 s16, 0
	v_mov_b32_e32 v158, v52
	v_mov_b32_e32 v159, v54
	v_add_u32_e32 v54, s12, v49
	v_add_u32_e32 v52, s6, v0
	v_ashrrev_i32_e32 v55, 31, v54
	v_ashrrev_i32_e32 v53, 31, v52
	v_lshlrev_b64 v[54:55], 12, v[54:55]
	v_lshlrev_b64 v[52:53], 12, v[52:53]
	v_lshl_add_u64 v[54:55], v[50:51], 0, v[54:55]
	v_lshl_add_u64 v[52:53], v[50:51], 0, v[52:53]
	global_load_dword v144, v[54:55], off
	global_load_dword v145, v[52:53], off
	v_mad_u64_u32 v[52:53], s[18:19], v49, s53, v[6:7]
	v_mad_u64_u32 v[54:55], s[18:19], v0, s53, v[6:7]
	v_or_b32_e32 v49, s11, v2
	v_or_b32_e32 v0, s10, v3
	v_mov_b32_e32 v160, v52
	v_mov_b32_e32 v161, v54
	v_add_u32_e32 v54, s12, v49
	v_add_u32_e32 v52, s6, v0
	v_ashrrev_i32_e32 v55, 31, v54
	v_ashrrev_i32_e32 v53, 31, v52
	v_lshlrev_b64 v[54:55], 12, v[54:55]
	v_lshlrev_b64 v[52:53], 12, v[52:53]
	v_lshl_add_u64 v[54:55], v[50:51], 0, v[54:55]
	v_lshl_add_u64 v[52:53], v[50:51], 0, v[52:53]
	global_load_dword v146, v[54:55], off
	global_load_dword v147, v[52:53], off
	v_mad_u64_u32 v[52:53], s[10:11], v49, s53, v[6:7]
	v_mad_u64_u32 v[54:55], s[10:11], v0, s53, v[6:7]
	v_mov_b32_e32 v162, v52
	v_mov_b32_e32 v163, v54
	s_waitcnt vmcnt(15)
	ds_write_b32 v148, v132
	s_waitcnt vmcnt(14)
	ds_write_b32 v149, v133
	s_waitcnt vmcnt(13)
	ds_write_b32 v150, v134
	s_waitcnt vmcnt(12)
	ds_write_b32 v151, v135
	s_waitcnt vmcnt(11)
	ds_write_b32 v152, v136
	s_waitcnt vmcnt(10)
	ds_write_b32 v153, v137
	s_waitcnt vmcnt(9)
	ds_write_b32 v154, v138
	s_waitcnt vmcnt(8)
	ds_write_b32 v155, v139
	s_waitcnt vmcnt(7)
	ds_write_b32 v156, v140
	s_waitcnt vmcnt(6)
	ds_write_b32 v157, v141
	s_waitcnt vmcnt(5)
	ds_write_b32 v158, v142
	s_waitcnt vmcnt(4)
	ds_write_b32 v159, v143
	s_waitcnt vmcnt(3)
	ds_write_b32 v160, v144
	s_waitcnt vmcnt(2)
	ds_write_b32 v161, v145
	s_waitcnt vmcnt(1)
	ds_write_b32 v162, v146
	s_waitcnt vmcnt(0)
	ds_write_b32 v163, v147
	s_cbranch_scc1 .LBB0_1446
; #define LAS __attribute__((address_space(3)))
; __device__ __forceinline__ unsigned cvt_pk_bf16(float lo, float hi) { f32x2_t v = {lo, hi}; bf16x2_t b = __builtin_convertvector(v, bf16x2_t); return __builtin_bit_cast(unsigned, b); }
; #define LDS_WAIT() asm volatile("s_waitcnt lgkmcnt(0)" ::: "memory")
; __device__ __forceinline__ void tr_item(const float* W, int ldw, int src_col, int nvalid, int k0, bf16_t* WT, int ldt, int dst_row, int dst_k, LAS float* scr, int lane) {
;     ...
;     LDS_WAIT();
;     const int c = lane & 7;
; #pragma unroll
;     for (int j = 0; j < 4; ++j) { const int n = (lane >> 3) + 8 * j; const LAS float* s = scr + (8 * c) * 33 + n;
;         u32x4 o; o.x = cvt_pk_bf16(s[0 * 33], s[1 * 33]); o.y = cvt_pk_bf16(s[2 * 33], s[3 * 33]); o.z = cvt_pk_bf16(s[4 * 33], s[5 * 33]); o.w = cvt_pk_bf16(s[6 * 33], s[7 * 33]);
;         *(u32x4*)(WT + (size_t)(dst_row + n) * ldt + dst_k + k0 + 8 * c) = o; }
;     LDS_WAIT();
	s_waitcnt lgkmcnt(0)
	ds_read2_b32 v[56:57], v7 offset0:33 offset1:41
	ds_read2_b32 v[58:59], v7 offset1:8
	ds_read2_b32 v[60:61], v7 offset0:66 offset1:74
	ds_read2_b32 v[62:63], v7 offset0:99 offset1:107
	ds_read2_b32 v[64:65], v7 offset0:132 offset1:140
	ds_read2_b32 v[78:79], v7 offset0:165 offset1:173
	ds_read2_b32 v[80:81], v7 offset0:198 offset1:206
	ds_read2_b32 v[82:83], v7 offset0:231 offset1:239
	s_mov_b32 s13, s7
	v_or_b32_e32 v0, s2, v5
	v_lshl_add_u64 v[54:55], s[12:13], 1, v[20:21]
	v_lshlrev_b32_e32 v0, 11, v0
	v_lshl_add_u64 v[84:85], v[54:55], 0, v[0:1]
	v_or_b32_e32 v0, s2, v35
	s_waitcnt lgkmcnt(6)
	v_cvt_pk_bf16_f32 v50, v58, v56
	s_waitcnt lgkmcnt(4)
	v_cvt_pk_bf16_f32 v51, v60, v62
	s_waitcnt lgkmcnt(2)
	v_cvt_pk_bf16_f32 v52, v64, v78
	s_waitcnt lgkmcnt(0)
	v_cvt_pk_bf16_f32 v53, v80, v82
	v_lshlrev_b32_e32 v0, 11, v0
	global_store_dwordx4 v[84:85], v[50:53], off
	s_nop 1
	v_cvt_pk_bf16_f32 v50, v59, v57
	v_cvt_pk_bf16_f32 v51, v61, v63
	v_cvt_pk_bf16_f32 v52, v65, v79
	v_cvt_pk_bf16_f32 v53, v81, v83
	v_lshl_add_u64 v[56:57], v[54:55], 0, v[0:1]
	global_store_dwordx4 v[56:57], v[50:53], off
	ds_read2_b32 v[56:57], v7 offset0:49 offset1:57
	ds_read2_b32 v[58:59], v7 offset0:16 offset1:24
	ds_read2_b32 v[60:61], v7 offset0:82 offset1:90
	ds_read2_b32 v[62:63], v7 offset0:115 offset1:123
	ds_read2_b32 v[64:65], v7 offset0:148 offset1:156
	ds_read2_b32 v[78:79], v7 offset0:181 offset1:189
	ds_read2_b32 v[80:81], v7 offset0:214 offset1:222
	ds_read2_b32 v[82:83], v7 offset0:247 offset1:255
	v_or_b32_e32 v0, s2, v67
	v_lshlrev_b32_e32 v0, 11, v0
	v_lshl_add_u64 v[84:85], v[54:55], 0, v[0:1]
	v_or_b32_e32 v0, s2, v68
	s_waitcnt lgkmcnt(6)
	v_cvt_pk_bf16_f32 v50, v58, v56
	s_waitcnt lgkmcnt(4)
	v_cvt_pk_bf16_f32 v51, v60, v62
	s_waitcnt lgkmcnt(2)
	v_cvt_pk_bf16_f32 v52, v64, v78
	s_waitcnt lgkmcnt(0)
	v_cvt_pk_bf16_f32 v53, v80, v82
	v_lshlrev_b32_e32 v0, 11, v0
	global_store_dwordx4 v[84:85], v[50:53], off
	v_lshl_add_u64 v[54:55], v[54:55], 0, v[0:1]
	s_nop 0
	v_cvt_pk_bf16_f32 v50, v59, v57
	v_cvt_pk_bf16_f32 v51, v61, v63
	v_cvt_pk_bf16_f32 v52, v65, v79
	v_cvt_pk_bf16_f32 v53, v81, v83
	global_store_dwordx4 v[54:55], v[50:53], off
	s_waitcnt lgkmcnt(0)

; #define LAS __attribute__((address_space(3)))
; #define LDS_WAIT() asm volatile("s_waitcnt lgkmcnt(0)" ::: "memory")
; __device__ __forceinline__ void tr_item(const float* W, int ldw, int src_col, int nvalid, int k0, bf16_t* WT, int ldt, int dst_row, int dst_k, LAS float* scr, int lane) {
; #pragma unroll 8
;     for (int i = 0; i < 32; ++i) { const int kk = 2 * i + (lane >> 5), c = lane & 31; scr[kk * 33 + c] = (c < nvalid) ? W[(size_t)(k0 + kk) * ldw + src_col + c] : 0.f; }
;     LDS_WAIT();
.LBB0_1451:
	s_lshl_b32 s11, s16, 1
	s_lshl_b32 s10, s6, 1
	v_or_b32_e32 v56, s11, v2
	v_or_b32_e32 v49, s10, v3
	v_add_u32_e32 v0, s12, v56
	v_add_u32_e32 v52, s13, v49
	v_mov_b32_e32 v53, v1
	v_lshlrev_b64 v[54:55], 12, v[0:1]
	v_lshlrev_b64 v[52:53], 12, v[52:53]
	v_lshl_add_u64 v[54:55], v[50:51], 0, v[54:55]
	v_lshl_add_u64 v[52:53], v[50:51], 0, v[52:53]
	global_load_dword v132, v[54:55], off
	global_load_dword v133, v[52:53], off
	v_mad_u64_u32 v[52:53], s[18:19], v56, s53, v[6:7]
	v_mad_u64_u32 v[54:55], s[18:19], v49, s53, v[6:7]
	s_add_i32 s19, s11, 4
	s_add_i32 s18, s10, 4
	v_or_b32_e32 v56, s19, v2
	v_or_b32_e32 v49, s18, v3
	v_mov_b32_e32 v53, v1
	s_add_i32 s16, s16, 16
	s_add_i32 s6, s6, 16
	s_add_i32 s17, s17, -16
	v_mov_b32_e32 v148, v52
	v_mov_b32_e32 v149, v54
	v_add_u32_e32 v0, s12, v56
	v_add_u32_e32 v52, s13, v49
	v_lshlrev_b64 v[54:55], 12, v[0:1]
	v_lshlrev_b64 v[52:53], 12, v[52:53]
	v_lshl_add_u64 v[54:55], v[50:51], 0, v[54:55]
	v_lshl_add_u64 v[52:53], v[50:51], 0, v[52:53]
	global_load_dword v134, v[54:55], off
	global_load_dword v135, v[52:53], off
	v_mad_u64_u32 v[52:53], s[18:19], v56, s53, v[6:7]
	v_mad_u64_u32 v[54:55], s[18:19], v49, s53, v[6:7]
	s_add_i32 s19, s11, 8
	s_add_i32 s18, s10, 8
	v_or_b32_e32 v56, s19, v2
	v_or_b32_e32 v49, s18, v3
	v_mov_b32_e32 v53, v1
	v_mov_b32_e32 v150, v52
	v_mov_b32_e32 v151, v54
	v_add_u32_e32 v0, s12, v56
	v_add_u32_e32 v52, s13, v49
	v_lshlrev_b64 v[54:55], 12, v[0:1]
	v_lshlrev_b64 v[52:53], 12, v[52:53]
	v_lshl_add_u64 v[54:55], v[50:51], 0, v[54:55]
	v_lshl_add_u64 v[52:53], v[50:51], 0, v[52:53]
	global_load_dword v136, v[54:55], off
	global_load_dword v137, v[52:53], off
	v_mad_u64_u32 v[52:53], s[18:19], v56, s53, v[6:7]
	v_mad_u64_u32 v[54:55], s[18:19], v49, s53, v[6:7]
	s_add_i32 s19, s11, 12
	s_add_i32 s18, s10, 12
	v_or_b32_e32 v56, s19, v2
	v_or_b32_e32 v49, s18, v3
	v_mov_b32_e32 v53, v1
	v_mov_b32_e32 v152, v52
	v_mov_b32_e32 v153, v54
	v_add_u32_e32 v0, s12, v56
	v_add_u32_e32 v52, s13, v49
	v_lshlrev_b64 v[54:55], 12, v[0:1]
	v_lshlrev_b64 v[52:53], 12, v[52:53]
	v_lshl_add_u64 v[54:55], v[50:51], 0, v[54:55]
	v_lshl_add_u64 v[52:53], v[50:51], 0, v[52:53]
	global_load_dword v138, v[54:55], off
	global_load_dword v139, v[52:53], off
	v_mad_u64_u32 v[52:53], s[18:19], v56, s53, v[6:7]
	v_mad_u64_u32 v[54:55], s[18:19], v49, s53, v[6:7]
	s_add_i32 s19, s11, 16
	s_add_i32 s18, s10, 16
	v_or_b32_e32 v56, s19, v2
	v_or_b32_e32 v49, s18, v3
	v_mov_b32_e32 v53, v1
	v_mov_b32_e32 v154, v52
	v_mov_b32_e32 v155, v54
	v_add_u32_e32 v0, s12, v56
	v_add_u32_e32 v52, s13, v49
	v_lshlrev_b64 v[54:55], 12, v[0:1]
	v_lshlrev_b64 v[52:53], 12, v[52:53]
	v_lshl_add_u64 v[54:55], v[50:51], 0, v[54:55]
	v_lshl_add_u64 v[52:53], v[50:51], 0, v[52:53]
	global_load_dword v140, v[54:55], off
	global_load_dword v141, v[52:53], off
	v_mad_u64_u32 v[52:53], s[18:19], v56, s53, v[6:7]
	v_mad_u64_u32 v[54:55], s[18:19], v49, s53, v[6:7]
	s_add_i32 s19, s11, 20
	s_add_i32 s18, s10, 20
	v_or_b32_e32 v56, s19, v2
	v_or_b32_e32 v49, s18, v3
	v_mov_b32_e32 v53, v1
	v_mov_b32_e32 v156, v52
	v_mov_b32_e32 v157, v54
	v_add_u32_e32 v0, s12, v56
	v_add_u32_e32 v52, s13, v49
	v_lshlrev_b64 v[54:55], 12, v[0:1]
	v_lshlrev_b64 v[52:53], 12, v[52:53]
	v_lshl_add_u64 v[54:55], v[50:51], 0, v[54:55]
	v_lshl_add_u64 v[52:53], v[50:51], 0, v[52:53]
	global_load_dword v142, v[54:55], off
	global_load_dword v143, v[52:53], off
	v_mad_u64_u32 v[52:53], s[18:19], v56, s53, v[6:7]
	v_mad_u64_u32 v[54:55], s[18:19], v49, s53, v[6:7]
	s_add_i32 s19, s11, 24
	s_add_i32 s18, s10, 24
	v_or_b32_e32 v56, s19, v2
	v_or_b32_e32 v49, s18, v3
	v_mov_b32_e32 v53, v1
	s_add_i32 s11, s11, 28
	s_add_i32 s10, s10, 28
	s_cmp_lg_u32 s17, 0
	v_mov_b32_e32 v158, v52
	v_mov_b32_e32 v159, v54
	v_add_u32_e32 v0, s12, v56
	v_add_u32_e32 v52, s13, v49
	v_lshlrev_b64 v[54:55], 12, v[0:1]
	v_lshlrev_b64 v[52:53], 12, v[52:53]
	v_lshl_add_u64 v[54:55], v[50:51], 0, v[54:55]
	v_lshl_add_u64 v[52:53], v[50:51], 0, v[52:53]
	global_load_dword v144, v[54:55], off
	global_load_dword v145, v[52:53], off
	v_mad_u64_u32 v[52:53], s[18:19], v56, s53, v[6:7]
	v_or_b32_e32 v56, s11, v2
	v_mad_u64_u32 v[54:55], s[18:19], v49, s53, v[6:7]
	v_or_b32_e32 v49, s10, v3
	v_mov_b32_e32 v53, v1
	v_mov_b32_e32 v160, v52
	v_mov_b32_e32 v161, v54
	v_add_u32_e32 v0, s12, v56
	v_add_u32_e32 v52, s13, v49
	v_lshlrev_b64 v[54:55], 12, v[0:1]
	v_lshlrev_b64 v[52:53], 12, v[52:53]
	v_lshl_add_u64 v[54:55], v[50:51], 0, v[54:55]
	v_lshl_add_u64 v[52:53], v[50:51], 0, v[52:53]
	global_load_dword v146, v[54:55], off
	global_load_dword v147, v[52:53], off
	v_mad_u64_u32 v[52:53], s[10:11], v56, s53, v[6:7]
	v_mad_u64_u32 v[54:55], s[10:11], v49, s53, v[6:7]
	v_mov_b32_e32 v162, v52
	v_mov_b32_e32 v163, v54
	s_waitcnt vmcnt(15)
	ds_write_b32 v148, v132
	s_waitcnt vmcnt(14)
	ds_write_b32 v149, v133
	s_waitcnt vmcnt(13)
	ds_write_b32 v150, v134
	s_waitcnt vmcnt(12)
	ds_write_b32 v151, v135
	s_waitcnt vmcnt(11)
	ds_write_b32 v152, v136
	s_waitcnt vmcnt(10)
	ds_write_b32 v153, v137
	s_waitcnt vmcnt(9)
	ds_write_b32 v154, v138
	s_waitcnt vmcnt(8)
	ds_write_b32 v155, v139
	s_waitcnt vmcnt(7)
	ds_write_b32 v156, v140
	s_waitcnt vmcnt(6)
	ds_write_b32 v157, v141
	s_waitcnt vmcnt(5)
	ds_write_b32 v158, v142
	s_waitcnt vmcnt(4)
	ds_write_b32 v159, v143
	s_waitcnt vmcnt(3)
	ds_write_b32 v160, v144
	s_waitcnt vmcnt(2)
	ds_write_b32 v161, v145
	s_waitcnt vmcnt(1)
	ds_write_b32 v162, v146
	s_waitcnt vmcnt(0)
	ds_write_b32 v163, v147
	s_cbranch_scc1 .LBB0_1451
; #define LAS __attribute__((address_space(3)))
; __device__ __forceinline__ unsigned cvt_pk_bf16(float lo, float hi) { f32x2_t v = {lo, hi}; bf16x2_t b = __builtin_convertvector(v, bf16x2_t); return __builtin_bit_cast(unsigned, b); }
; #define LDS_WAIT() asm volatile("s_waitcnt lgkmcnt(0)" ::: "memory")
; __device__ __forceinline__ void tr_item(const float* W, int ldw, int src_col, int nvalid, int k0, bf16_t* WT, int ldt, int dst_row, int dst_k, LAS float* scr, int lane) {
;     ...
;     LDS_WAIT();
;     const int c = lane & 7;
; #pragma unroll
;     for (int j = 0; j < 4; ++j) { const int n = (lane >> 3) + 8 * j; const LAS float* s = scr + (8 * c) * 33 + n;
;         u32x4 o; o.x = cvt_pk_bf16(s[0 * 33], s[1 * 33]); o.y = cvt_pk_bf16(s[2 * 33], s[3 * 33]); o.z = cvt_pk_bf16(s[4 * 33], s[5 * 33]); o.w = cvt_pk_bf16(s[6 * 33], s[7 * 33]);
;         *(u32x4*)(WT + (size_t)(dst_row + n) * ldt + dst_k + k0 + 8 * c) = o; }
;     LDS_WAIT();
	s_lshl_b32 s3, s3, 10
	s_waitcnt lgkmcnt(0)
	s_add_u32 s3, s8, s3
	s_addc_u32 s6, s9, 0
	s_lshl_b32 s10, s12, 1
	ds_read2_b32 v[56:57], v7 offset0:33 offset1:41
	ds_read2_b32 v[58:59], v7 offset1:8
	ds_read2_b32 v[60:61], v7 offset0:66 offset1:74
	ds_read2_b32 v[62:63], v7 offset0:99 offset1:107
	ds_read2_b32 v[64:65], v7 offset0:132 offset1:140
	ds_read2_b32 v[78:79], v7 offset0:165 offset1:173
	ds_read2_b32 v[80:81], v7 offset0:198 offset1:206
	ds_read2_b32 v[82:83], v7 offset0:231 offset1:239
	s_add_u32 s10, s3, s10
	s_addc_u32 s11, s6, 0
	v_mov_b32_e32 v49, v1
	v_or_b32_e32 v0, s2, v5
	v_lshl_add_u64 v[54:55], s[10:11], 0, v[48:49]
	v_mul_u32_u24_e32 v0, 0xc00, v0
	v_lshl_add_u64 v[84:85], v[54:55], 0, v[0:1]
	v_or_b32_e32 v0, s2, v35
	s_waitcnt lgkmcnt(6)
	v_cvt_pk_bf16_f32 v50, v58, v56
	s_waitcnt lgkmcnt(4)
	v_cvt_pk_bf16_f32 v51, v60, v62
	s_waitcnt lgkmcnt(2)
	v_cvt_pk_bf16_f32 v52, v64, v78
	s_waitcnt lgkmcnt(0)
	v_cvt_pk_bf16_f32 v53, v80, v82
	v_mul_u32_u24_e32 v0, 0xc00, v0
	global_store_dwordx4 v[84:85], v[50:53], off
	v_readlane_b32 s24, v254, 39
	v_readlane_b32 s28, v254, 43
	v_cvt_pk_bf16_f32 v50, v59, v57
	v_cvt_pk_bf16_f32 v51, v61, v63
	v_cvt_pk_bf16_f32 v52, v65, v79
	v_cvt_pk_bf16_f32 v53, v81, v83
	v_lshl_add_u64 v[56:57], v[54:55], 0, v[0:1]
	global_store_dwordx4 v[56:57], v[50:53], off
	ds_read2_b32 v[56:57], v7 offset0:16 offset1:24
	ds_read2_b32 v[58:59], v7 offset0:49 offset1:57
	ds_read2_b32 v[60:61], v7 offset0:82 offset1:90
	ds_read2_b32 v[62:63], v7 offset0:115 offset1:123
	ds_read2_b32 v[64:65], v7 offset0:148 offset1:156
	ds_read2_b32 v[78:79], v7 offset0:181 offset1:189
	ds_read2_b32 v[80:81], v7 offset0:214 offset1:222
	ds_read2_b32 v[82:83], v7 offset0:247 offset1:255
	v_or_b32_e32 v0, s2, v67
	v_mul_u32_u24_e32 v0, 0xc00, v0
	v_lshl_add_u64 v[84:85], v[54:55], 0, v[0:1]
	v_or_b32_e32 v0, s2, v68
	s_waitcnt lgkmcnt(6)
	v_cvt_pk_bf16_f32 v50, v56, v58
	s_waitcnt lgkmcnt(4)
	v_cvt_pk_bf16_f32 v51, v60, v62
	s_waitcnt lgkmcnt(2)
	v_cvt_pk_bf16_f32 v52, v64, v78
	s_waitcnt lgkmcnt(0)
	v_cvt_pk_bf16_f32 v53, v80, v82
	v_mul_u32_u24_e32 v0, 0xc00, v0
	global_store_dwordx4 v[84:85], v[50:53], off
	v_lshl_add_u64 v[54:55], v[54:55], 0, v[0:1]
	v_readlane_b32 s25, v254, 40
	v_cvt_pk_bf16_f32 v50, v57, v59
	v_cvt_pk_bf16_f32 v51, v61, v63
	v_cvt_pk_bf16_f32 v52, v65, v79
	v_cvt_pk_bf16_f32 v53, v81, v83
	global_store_dwordx4 v[54:55], v[50:53], off
	s_waitcnt lgkmcnt(0)
	v_readlane_b32 s29, v254, 44

; #define LAS __attribute__((address_space(3)))
; #define LDS_WAIT() asm volatile("s_waitcnt lgkmcnt(0)" ::: "memory")
; __device__ __forceinline__ void tr_item(const float* W, int ldw, int src_col, int nvalid, int k0, bf16_t* WT, int ldt, int dst_row, int dst_k, LAS float* scr, int lane) {
; #pragma unroll 8
;     for (int i = 0; i < 32; ++i) { const int kk = 2 * i + (lane >> 5), c = lane & 31; scr[kk * 33 + c] = (c < nvalid) ? W[(size_t)(k0 + kk) * ldw + src_col + c] : 0.f; }
;     LDS_WAIT();
.LBB0_1456:
	s_lshl_b32 s16, s11, 1
	s_lshl_b32 s13, s10, 1
	v_or_b32_e32 v49, s16, v2
	v_or_b32_e32 v0, s13, v3
	v_add_u32_e32 v52, s2, v49
	v_add_u32_e32 v54, s6, v0
	v_mad_u64_u32 v[52:53], s[18:19], v52, s33, v[50:51]
	v_mad_u64_u32 v[54:55], s[18:19], v54, s33, v[50:51]
	global_load_dword v132, v[52:53], off
	global_load_dword v133, v[54:55], off
	v_mad_u64_u32 v[52:53], s[18:19], v49, s53, v[6:7]
	v_mad_u64_u32 v[54:55], s[18:19], v0, s53, v[6:7]
	s_add_i32 s18, s16, 4
	s_add_i32 s17, s13, 4
	v_or_b32_e32 v49, s18, v2
	v_or_b32_e32 v0, s17, v3
	s_add_i32 s17, s13, 8
	s_add_i32 s11, s11, 16
	s_add_i32 s10, s10, 16
	s_add_i32 s12, s12, -16
	v_mov_b32_e32 v148, v52
	v_mov_b32_e32 v149, v54
	v_add_u32_e32 v52, s2, v49
	v_add_u32_e32 v54, s6, v0
	v_mad_u64_u32 v[52:53], s[18:19], v52, s33, v[50:51]
	v_mad_u64_u32 v[54:55], s[18:19], v54, s33, v[50:51]
	global_load_dword v134, v[52:53], off
	global_load_dword v135, v[54:55], off
	v_mad_u64_u32 v[52:53], s[18:19], v49, s53, v[6:7]
	v_mad_u64_u32 v[54:55], s[18:19], v0, s53, v[6:7]
	s_add_i32 s18, s16, 8
	s_nop 0
	v_or_b32_e32 v49, s18, v2
	v_or_b32_e32 v0, s17, v3
	s_add_i32 s17, s13, 12
	v_mov_b32_e32 v150, v52
	v_mov_b32_e32 v151, v54
	v_add_u32_e32 v52, s2, v49
	v_add_u32_e32 v54, s6, v0
	v_mad_u64_u32 v[52:53], s[18:19], v52, s33, v[50:51]
	v_mad_u64_u32 v[54:55], s[18:19], v54, s33, v[50:51]
	global_load_dword v136, v[52:53], off
	global_load_dword v137, v[54:55], off
	v_mad_u64_u32 v[52:53], s[18:19], v49, s53, v[6:7]
	v_mad_u64_u32 v[54:55], s[18:19], v0, s53, v[6:7]
	s_add_i32 s18, s16, 12
	s_nop 0
	v_or_b32_e32 v49, s18, v2
	v_or_b32_e32 v0, s17, v3
	s_add_i32 s17, s13, 16
	v_mov_b32_e32 v152, v52
	v_mov_b32_e32 v153, v54
	v_add_u32_e32 v52, s2, v49
	v_add_u32_e32 v54, s6, v0
	v_mad_u64_u32 v[52:53], s[18:19], v52, s33, v[50:51]
	v_mad_u64_u32 v[54:55], s[18:19], v54, s33, v[50:51]
	global_load_dword v138, v[52:53], off
	global_load_dword v139, v[54:55], off
	v_mad_u64_u32 v[52:53], s[18:19], v49, s53, v[6:7]
	v_mad_u64_u32 v[54:55], s[18:19], v0, s53, v[6:7]
	s_add_i32 s18, s16, 16
	s_nop 0
	v_or_b32_e32 v49, s18, v2
	v_or_b32_e32 v0, s17, v3
	s_add_i32 s17, s13, 20
	v_mov_b32_e32 v154, v52
	v_mov_b32_e32 v155, v54
	v_add_u32_e32 v52, s2, v49
	v_add_u32_e32 v54, s6, v0
	v_mad_u64_u32 v[52:53], s[18:19], v52, s33, v[50:51]
	v_mad_u64_u32 v[54:55], s[18:19], v54, s33, v[50:51]
	global_load_dword v140, v[52:53], off
	global_load_dword v141, v[54:55], off
	v_mad_u64_u32 v[52:53], s[18:19], v49, s53, v[6:7]
	v_mad_u64_u32 v[54:55], s[18:19], v0, s53, v[6:7]
	s_add_i32 s18, s16, 20
	s_nop 0
	v_or_b32_e32 v49, s18, v2
	v_or_b32_e32 v0, s17, v3
	s_add_i32 s17, s13, 24
	s_add_i32 s13, s13, 28
	v_mov_b32_e32 v156, v52
	v_mov_b32_e32 v157, v54
	v_add_u32_e32 v52, s2, v49
	v_add_u32_e32 v54, s6, v0
	v_mad_u64_u32 v[52:53], s[18:19], v52, s33, v[50:51]
	v_mad_u64_u32 v[54:55], s[18:19], v54, s33, v[50:51]
	global_load_dword v142, v[52:53], off
	global_load_dword v143, v[54:55], off
	v_mad_u64_u32 v[52:53], s[18:19], v49, s53, v[6:7]
	v_mad_u64_u32 v[54:55], s[18:19], v0, s53, v[6:7]
	s_add_i32 s18, s16, 24
	s_nop 0
	v_or_b32_e32 v49, s18, v2
	v_or_b32_e32 v0, s17, v3
	s_add_i32 s16, s16, 28
	s_cmp_lg_u32 s12, 0
	v_mov_b32_e32 v158, v52
	v_mov_b32_e32 v159, v54
	v_add_u32_e32 v52, s2, v49
	v_add_u32_e32 v54, s6, v0
	v_mad_u64_u32 v[52:53], s[18:19], v52, s33, v[50:51]
	v_mad_u64_u32 v[54:55], s[18:19], v54, s33, v[50:51]
	global_load_dword v144, v[52:53], off
	global_load_dword v145, v[54:55], off
	v_mad_u64_u32 v[52:53], s[18:19], v49, s53, v[6:7]
	v_or_b32_e32 v49, s16, v2
	v_mad_u64_u32 v[54:55], s[18:19], v0, s53, v[6:7]
	v_or_b32_e32 v0, s13, v3
	v_mov_b32_e32 v160, v52
	v_mov_b32_e32 v161, v54
	v_add_u32_e32 v52, s2, v49
	v_add_u32_e32 v54, s6, v0
	v_mad_u64_u32 v[52:53], s[16:17], v52, s33, v[50:51]
	v_mad_u64_u32 v[54:55], s[16:17], v54, s33, v[50:51]
	global_load_dword v146, v[52:53], off
	global_load_dword v147, v[54:55], off
	v_mad_u64_u32 v[52:53], s[16:17], v49, s53, v[6:7]
	v_mad_u64_u32 v[54:55], s[16:17], v0, s53, v[6:7]
	v_mov_b32_e32 v162, v52
	v_mov_b32_e32 v163, v54
	s_waitcnt vmcnt(15)
	ds_write_b32 v148, v132
	s_waitcnt vmcnt(14)
	ds_write_b32 v149, v133
	s_waitcnt vmcnt(13)
	ds_write_b32 v150, v134
	s_waitcnt vmcnt(12)
	ds_write_b32 v151, v135
	s_waitcnt vmcnt(11)
	ds_write_b32 v152, v136
	s_waitcnt vmcnt(10)
	ds_write_b32 v153, v137
	s_waitcnt vmcnt(9)
	ds_write_b32 v154, v138
	s_waitcnt vmcnt(8)
	ds_write_b32 v155, v139
	s_waitcnt vmcnt(7)
	ds_write_b32 v156, v140
	s_waitcnt vmcnt(6)
	ds_write_b32 v157, v141
	s_waitcnt vmcnt(5)
	ds_write_b32 v158, v142
	s_waitcnt vmcnt(4)
	ds_write_b32 v159, v143
	s_waitcnt vmcnt(3)
	ds_write_b32 v160, v144
	s_waitcnt vmcnt(2)
	ds_write_b32 v161, v145
	s_waitcnt vmcnt(1)
	ds_write_b32 v162, v146
	s_waitcnt vmcnt(0)
	ds_write_b32 v163, v147
	s_cbranch_scc1 .LBB0_1456
; #define LAS __attribute__((address_space(3)))
; __device__ __forceinline__ unsigned cvt_pk_bf16(float lo, float hi) { f32x2_t v = {lo, hi}; bf16x2_t b = __builtin_convertvector(v, bf16x2_t); return __builtin_bit_cast(unsigned, b); }
; #define LDS_WAIT() asm volatile("s_waitcnt lgkmcnt(0)" ::: "memory")
; __device__ __forceinline__ void tr_item(const float* W, int ldw, int src_col, int nvalid, int k0, bf16_t* WT, int ldt, int dst_row, int dst_k, LAS float* scr, int lane) {
;     ...
;     LDS_WAIT();
;     const int c = lane & 7;
; #pragma unroll
;     for (int j = 0; j < 4; ++j) { const int n = (lane >> 3) + 8 * j; const LAS float* s = scr + (8 * c) * 33 + n;
;         u32x4 o; o.x = cvt_pk_bf16(s[0 * 33], s[1 * 33]); o.y = cvt_pk_bf16(s[2 * 33], s[3 * 33]); o.z = cvt_pk_bf16(s[4 * 33], s[5 * 33]); o.w = cvt_pk_bf16(s[6 * 33], s[7 * 33]);
;         *(u32x4*)(WT + (size_t)(dst_row + n) * ldt + dst_k + k0 + 8 * c) = o; }
;     LDS_WAIT();
	s_waitcnt lgkmcnt(0)
	ds_read2_b32 v[56:57], v7 offset0:33 offset1:41
	ds_read2_b32 v[58:59], v7 offset1:8
	ds_read2_b32 v[60:61], v7 offset0:66 offset1:74
	ds_read2_b32 v[62:63], v7 offset0:99 offset1:107
	ds_read2_b32 v[64:65], v7 offset0:132 offset1:140
	ds_read2_b32 v[78:79], v7 offset0:165 offset1:173
	ds_read2_b32 v[80:81], v7 offset0:198 offset1:206
	ds_read2_b32 v[82:83], v7 offset0:231 offset1:239
	s_and_b32 s3, 0xffff, s3
	s_and_b32 s2, 0xffff, s2
	s_lshl_b32 s6, s2, 1
	v_or_b32_e32 v0, s3, v5
	v_lshl_add_u64 v[54:55], v[22:23], 0, s[6:7]
	v_lshlrev_b32_e32 v0, 11, v0
	v_lshl_add_u64 v[84:85], v[54:55], 0, v[0:1]
	v_or_b32_e32 v0, s3, v35
	s_waitcnt lgkmcnt(6)
	v_cvt_pk_bf16_f32 v50, v58, v56
	s_waitcnt lgkmcnt(4)
	v_cvt_pk_bf16_f32 v51, v60, v62
	s_waitcnt lgkmcnt(2)
	v_cvt_pk_bf16_f32 v52, v64, v78
	s_waitcnt lgkmcnt(0)
	v_cvt_pk_bf16_f32 v53, v80, v82
	v_lshlrev_b32_e32 v0, 11, v0
	global_store_dwordx4 v[84:85], v[50:53], off
	v_readlane_b32 s40, v254, 0
	v_readlane_b32 s44, v254, 48
	v_cvt_pk_bf16_f32 v50, v59, v57
	v_cvt_pk_bf16_f32 v51, v61, v63
	v_cvt_pk_bf16_f32 v52, v65, v79
	v_cvt_pk_bf16_f32 v53, v81, v83
	v_lshl_add_u64 v[56:57], v[54:55], 0, v[0:1]
	global_store_dwordx4 v[56:57], v[50:53], off
	ds_read2_b32 v[56:57], v7 offset0:49 offset1:57
	ds_read2_b32 v[58:59], v7 offset0:16 offset1:24
	ds_read2_b32 v[60:61], v7 offset0:82 offset1:90
	ds_read2_b32 v[62:63], v7 offset0:115 offset1:123
	ds_read2_b32 v[64:65], v7 offset0:148 offset1:156
	ds_read2_b32 v[78:79], v7 offset0:181 offset1:189
	ds_read2_b32 v[80:81], v7 offset0:214 offset1:222
	ds_read2_b32 v[82:83], v7 offset0:247 offset1:255
	v_or_b32_e32 v0, s3, v67
	v_lshlrev_b32_e32 v0, 11, v0
	v_lshl_add_u64 v[84:85], v[54:55], 0, v[0:1]
	v_or_b32_e32 v0, s3, v68
	s_waitcnt lgkmcnt(6)
	v_cvt_pk_bf16_f32 v50, v58, v56
	s_waitcnt lgkmcnt(4)
	v_cvt_pk_bf16_f32 v51, v60, v62
	s_waitcnt lgkmcnt(2)
	v_cvt_pk_bf16_f32 v52, v64, v78
	s_waitcnt lgkmcnt(0)
	v_cvt_pk_bf16_f32 v53, v80, v82
	v_lshlrev_b32_e32 v0, 11, v0
	global_store_dwordx4 v[84:85], v[50:53], off
	v_lshl_add_u64 v[54:55], v[54:55], 0, v[0:1]
	v_readlane_b32 s50, v254, 53
	v_cvt_pk_bf16_f32 v50, v59, v57
	v_cvt_pk_bf16_f32 v51, v61, v63
	v_cvt_pk_bf16_f32 v52, v65, v79
	v_cvt_pk_bf16_f32 v53, v81, v83
	global_store_dwordx4 v[54:55], v[50:53], off
	s_waitcnt lgkmcnt(0)
	v_readlane_b32 s24, v254, 39
	v_readlane_b32 s28, v254, 43
	v_readlane_b32 s42, v253, 46
	v_readlane_b32 s41, v254, 1
	v_readlane_b32 s43, v254, 47
	v_readlane_b32 s45, v254, 49
	v_readlane_b32 s46, v254, 50
	v_readlane_b32 s48, v254, 51
	v_readlane_b32 s51, v254, 54
	v_readlane_b32 s47, v254, 55
	v_readlane_b32 s25, v254, 40
	v_readlane_b32 s36, v254, 62
	v_readlane_b32 s29, v254, 44
	v_readlane_b32 s49, v254, 52

; #define LAS __attribute__((address_space(3)))
; #define LDS_WAIT() asm volatile("s_waitcnt lgkmcnt(0)" ::: "memory")
; __device__ __forceinline__ void tr_item(const float* W, int ldw, int src_col, int nvalid, int k0, bf16_t* WT, int ldt, int dst_row, int dst_k, LAS float* scr, int lane) {
; #pragma unroll 8
;     for (int i = 0; i < 32; ++i) { const int kk = 2 * i + (lane >> 5), c = lane & 31; scr[kk * 33 + c] = (c < nvalid) ? W[(size_t)(k0 + kk) * ldw + src_col + c] : 0.f; }
;     LDS_WAIT();
.LBB0_1491:
	s_lshl_b32 s11, s13, 1
	s_lshl_b32 s10, s3, 1
	v_or_b32_e32 v49, s11, v2
	v_or_b32_e32 v0, s10, v3
	v_add_u32_e32 v54, s12, v49
	v_add_u32_e32 v52, s6, v0
	v_ashrrev_i32_e32 v55, 31, v54
	v_ashrrev_i32_e32 v53, 31, v52
	v_lshlrev_b64 v[54:55], 12, v[54:55]
	v_lshlrev_b64 v[52:53], 12, v[52:53]
	v_lshl_add_u64 v[54:55], v[50:51], 0, v[54:55]
	v_lshl_add_u64 v[52:53], v[50:51], 0, v[52:53]
	global_load_dword v132, v[54:55], off
	global_load_dword v133, v[52:53], off
	v_mad_u64_u32 v[52:53], s[18:19], v49, s53, v[6:7]
	v_mad_u64_u32 v[54:55], s[18:19], v0, s53, v[6:7]
	s_add_i32 s18, s11, 4
	s_add_i32 s17, s10, 4
	v_or_b32_e32 v49, s18, v2
	v_or_b32_e32 v0, s17, v3
	s_add_i32 s17, s10, 8
	s_add_i32 s13, s13, 16
	s_add_i32 s3, s3, 16
	s_add_i32 s16, s16, -16
	v_mov_b32_e32 v148, v52
	v_mov_b32_e32 v149, v54
	v_add_u32_e32 v54, s12, v49
	v_add_u32_e32 v52, s6, v0
	v_ashrrev_i32_e32 v55, 31, v54
	v_ashrrev_i32_e32 v53, 31, v52
	v_lshlrev_b64 v[54:55], 12, v[54:55]
	v_lshlrev_b64 v[52:53], 12, v[52:53]
	v_lshl_add_u64 v[54:55], v[50:51], 0, v[54:55]
	v_lshl_add_u64 v[52:53], v[50:51], 0, v[52:53]
	global_load_dword v134, v[54:55], off
	global_load_dword v135, v[52:53], off
	v_mad_u64_u32 v[52:53], s[18:19], v49, s53, v[6:7]
	v_mad_u64_u32 v[54:55], s[18:19], v0, s53, v[6:7]
	s_add_i32 s18, s11, 8
	s_nop 0
	v_or_b32_e32 v49, s18, v2
	v_or_b32_e32 v0, s17, v3
	s_add_i32 s17, s10, 12
	v_mov_b32_e32 v150, v52
	v_mov_b32_e32 v151, v54
	v_add_u32_e32 v54, s12, v49
	v_add_u32_e32 v52, s6, v0
	v_ashrrev_i32_e32 v55, 31, v54
	v_ashrrev_i32_e32 v53, 31, v52
	v_lshlrev_b64 v[54:55], 12, v[54:55]
	v_lshlrev_b64 v[52:53], 12, v[52:53]
	v_lshl_add_u64 v[54:55], v[50:51], 0, v[54:55]
	v_lshl_add_u64 v[52:53], v[50:51], 0, v[52:53]
	global_load_dword v136, v[54:55], off
	global_load_dword v137, v[52:53], off
	v_mad_u64_u32 v[52:53], s[18:19], v49, s53, v[6:7]
	v_mad_u64_u32 v[54:55], s[18:19], v0, s53, v[6:7]
	s_add_i32 s18, s11, 12
	s_nop 0
	v_or_b32_e32 v49, s18, v2
	v_or_b32_e32 v0, s17, v3
	s_add_i32 s17, s10, 16
	v_mov_b32_e32 v152, v52
	v_mov_b32_e32 v153, v54
	v_add_u32_e32 v54, s12, v49
	v_add_u32_e32 v52, s6, v0
	v_ashrrev_i32_e32 v55, 31, v54
	v_ashrrev_i32_e32 v53, 31, v52
	v_lshlrev_b64 v[54:55], 12, v[54:55]
	v_lshlrev_b64 v[52:53], 12, v[52:53]
	v_lshl_add_u64 v[54:55], v[50:51], 0, v[54:55]
	v_lshl_add_u64 v[52:53], v[50:51], 0, v[52:53]
	global_load_dword v138, v[54:55], off
	global_load_dword v139, v[52:53], off
	v_mad_u64_u32 v[52:53], s[18:19], v49, s53, v[6:7]
	v_mad_u64_u32 v[54:55], s[18:19], v0, s53, v[6:7]
	s_add_i32 s18, s11, 16
	s_nop 0
	v_or_b32_e32 v49, s18, v2
	v_or_b32_e32 v0, s17, v3
	s_add_i32 s17, s10, 20
	v_mov_b32_e32 v154, v52
	v_mov_b32_e32 v155, v54
	v_add_u32_e32 v54, s12, v49
	v_add_u32_e32 v52, s6, v0
	v_ashrrev_i32_e32 v55, 31, v54
	v_ashrrev_i32_e32 v53, 31, v52
	v_lshlrev_b64 v[54:55], 12, v[54:55]
	v_lshlrev_b64 v[52:53], 12, v[52:53]
	v_lshl_add_u64 v[54:55], v[50:51], 0, v[54:55]
	v_lshl_add_u64 v[52:53], v[50:51], 0, v[52:53]
	global_load_dword v140, v[54:55], off
	global_load_dword v141, v[52:53], off
	v_mad_u64_u32 v[52:53], s[18:19], v49, s53, v[6:7]
	v_mad_u64_u32 v[54:55], s[18:19], v0, s53, v[6:7]
	s_add_i32 s18, s11, 20
	s_nop 0
	v_or_b32_e32 v49, s18, v2
	v_or_b32_e32 v0, s17, v3
	s_add_i32 s17, s10, 24
	s_add_i32 s10, s10, 28
	v_mov_b32_e32 v156, v52
	v_mov_b32_e32 v157, v54
	v_add_u32_e32 v54, s12, v49
	v_add_u32_e32 v52, s6, v0
	v_ashrrev_i32_e32 v55, 31, v54
	v_ashrrev_i32_e32 v53, 31, v52
	v_lshlrev_b64 v[54:55], 12, v[54:55]
	v_lshlrev_b64 v[52:53], 12, v[52:53]
	v_lshl_add_u64 v[54:55], v[50:51], 0, v[54:55]
	v_lshl_add_u64 v[52:53], v[50:51], 0, v[52:53]
	global_load_dword v142, v[54:55], off
	global_load_dword v143, v[52:53], off
	v_mad_u64_u32 v[52:53], s[18:19], v49, s53, v[6:7]
	v_mad_u64_u32 v[54:55], s[18:19], v0, s53, v[6:7]
	s_add_i32 s18, s11, 24
	s_nop 0
	v_or_b32_e32 v49, s18, v2
	v_or_b32_e32 v0, s17, v3
	s_add_i32 s11, s11, 28
	s_cmp_lg_u32 s16, 0
	v_mov_b32_e32 v158, v52
	v_mov_b32_e32 v159, v54
	v_add_u32_e32 v54, s12, v49
	v_add_u32_e32 v52, s6, v0
	v_ashrrev_i32_e32 v55, 31, v54
	v_ashrrev_i32_e32 v53, 31, v52
	v_lshlrev_b64 v[54:55], 12, v[54:55]
	v_lshlrev_b64 v[52:53], 12, v[52:53]
	v_lshl_add_u64 v[54:55], v[50:51], 0, v[54:55]
	v_lshl_add_u64 v[52:53], v[50:51], 0, v[52:53]
	global_load_dword v144, v[54:55], off
	global_load_dword v145, v[52:53], off
	v_mad_u64_u32 v[52:53], s[18:19], v49, s53, v[6:7]
	v_mad_u64_u32 v[54:55], s[18:19], v0, s53, v[6:7]
	v_or_b32_e32 v49, s11, v2
	v_or_b32_e32 v0, s10, v3
	v_mov_b32_e32 v160, v52
	v_mov_b32_e32 v161, v54
	v_add_u32_e32 v54, s12, v49
	v_add_u32_e32 v52, s6, v0
	v_ashrrev_i32_e32 v55, 31, v54
	v_ashrrev_i32_e32 v53, 31, v52
	v_lshlrev_b64 v[54:55], 12, v[54:55]
	v_lshlrev_b64 v[52:53], 12, v[52:53]
	v_lshl_add_u64 v[54:55], v[50:51], 0, v[54:55]
	v_lshl_add_u64 v[52:53], v[50:51], 0, v[52:53]
	global_load_dword v146, v[54:55], off
	global_load_dword v147, v[52:53], off
	v_mad_u64_u32 v[52:53], s[10:11], v49, s53, v[6:7]
	v_mad_u64_u32 v[54:55], s[10:11], v0, s53, v[6:7]
	v_mov_b32_e32 v162, v52
	v_mov_b32_e32 v163, v54
	s_waitcnt vmcnt(15)
	ds_write_b32 v148, v132
	s_waitcnt vmcnt(14)
	ds_write_b32 v149, v133
	s_waitcnt vmcnt(13)
	ds_write_b32 v150, v134
	s_waitcnt vmcnt(12)
	ds_write_b32 v151, v135
	s_waitcnt vmcnt(11)
	ds_write_b32 v152, v136
	s_waitcnt vmcnt(10)
	ds_write_b32 v153, v137
	s_waitcnt vmcnt(9)
	ds_write_b32 v154, v138
	s_waitcnt vmcnt(8)
	ds_write_b32 v155, v139
	s_waitcnt vmcnt(7)
	ds_write_b32 v156, v140
	s_waitcnt vmcnt(6)
	ds_write_b32 v157, v141
	s_waitcnt vmcnt(5)
	ds_write_b32 v158, v142
	s_waitcnt vmcnt(4)
	ds_write_b32 v159, v143
	s_waitcnt vmcnt(3)
	ds_write_b32 v160, v144
	s_waitcnt vmcnt(2)
	ds_write_b32 v161, v145
	s_waitcnt vmcnt(1)
	ds_write_b32 v162, v146
	s_waitcnt vmcnt(0)
	ds_write_b32 v163, v147
	s_cbranch_scc1 .LBB0_1491
; #define LAS __attribute__((address_space(3)))
; __device__ __forceinline__ unsigned cvt_pk_bf16(float lo, float hi) { f32x2_t v = {lo, hi}; bf16x2_t b = __builtin_convertvector(v, bf16x2_t); return __builtin_bit_cast(unsigned, b); }
; #define LDS_WAIT() asm volatile("s_waitcnt lgkmcnt(0)" ::: "memory")
; __device__ __forceinline__ void tr_item(const float* W, int ldw, int src_col, int nvalid, int k0, bf16_t* WT, int ldt, int dst_row, int dst_k, LAS float* scr, int lane) {
;     ...
;     LDS_WAIT();
;     const int c = lane & 7;
; #pragma unroll
;     for (int j = 0; j < 4; ++j) { const int n = (lane >> 3) + 8 * j; const LAS float* s = scr + (8 * c) * 33 + n;
;         u32x4 o; o.x = cvt_pk_bf16(s[0 * 33], s[1 * 33]); o.y = cvt_pk_bf16(s[2 * 33], s[3 * 33]); o.z = cvt_pk_bf16(s[4 * 33], s[5 * 33]); o.w = cvt_pk_bf16(s[6 * 33], s[7 * 33]);
;         *(u32x4*)(WT + (size_t)(dst_row + n) * ldt + dst_k + k0 + 8 * c) = o; }
;     LDS_WAIT();
	s_waitcnt lgkmcnt(0)
	ds_read2_b32 v[56:57], v7 offset0:33 offset1:41
	ds_read2_b32 v[58:59], v7 offset1:8
	ds_read2_b32 v[60:61], v7 offset0:66 offset1:74
	ds_read2_b32 v[62:63], v7 offset0:99 offset1:107
	ds_read2_b32 v[64:65], v7 offset0:132 offset1:140
	ds_read2_b32 v[78:79], v7 offset0:165 offset1:173
	ds_read2_b32 v[80:81], v7 offset0:198 offset1:206
	ds_read2_b32 v[82:83], v7 offset0:231 offset1:239
	s_mov_b32 s13, s7
	v_or_b32_e32 v0, s2, v5
	v_lshl_add_u64 v[54:55], s[12:13], 1, v[26:27]
	v_mul_u32_u24_e32 v0, 0x1600, v0
	v_lshl_add_u64 v[84:85], v[54:55], 0, v[0:1]
	v_or_b32_e32 v0, s2, v35
	s_waitcnt lgkmcnt(6)
	v_cvt_pk_bf16_f32 v50, v58, v56
	s_waitcnt lgkmcnt(4)
	v_cvt_pk_bf16_f32 v51, v60, v62
	s_waitcnt lgkmcnt(2)
	v_cvt_pk_bf16_f32 v52, v64, v78
	s_waitcnt lgkmcnt(0)
	v_cvt_pk_bf16_f32 v53, v80, v82
	v_mul_u32_u24_e32 v0, 0x1600, v0
	global_store_dwordx4 v[84:85], v[50:53], off
	s_nop 1
	v_cvt_pk_bf16_f32 v50, v59, v57
	v_cvt_pk_bf16_f32 v51, v61, v63
	v_cvt_pk_bf16_f32 v52, v65, v79
	v_cvt_pk_bf16_f32 v53, v81, v83
	v_lshl_add_u64 v[56:57], v[54:55], 0, v[0:1]
	global_store_dwordx4 v[56:57], v[50:53], off
	ds_read2_b32 v[56:57], v7 offset0:16 offset1:24
	ds_read2_b32 v[58:59], v7 offset0:49 offset1:57
	ds_read2_b32 v[60:61], v7 offset0:82 offset1:90
	ds_read2_b32 v[62:63], v7 offset0:115 offset1:123
	ds_read2_b32 v[64:65], v7 offset0:148 offset1:156
	ds_read2_b32 v[78:79], v7 offset0:181 offset1:189
	ds_read2_b32 v[80:81], v7 offset0:214 offset1:222
	ds_read2_b32 v[82:83], v7 offset0:247 offset1:255
	v_or_b32_e32 v0, s2, v67
	v_mul_u32_u24_e32 v0, 0x1600, v0
	v_lshl_add_u64 v[84:85], v[54:55], 0, v[0:1]
	v_or_b32_e32 v0, s2, v68
	s_waitcnt lgkmcnt(6)
	v_cvt_pk_bf16_f32 v50, v56, v58
	s_waitcnt lgkmcnt(4)
	v_cvt_pk_bf16_f32 v51, v60, v62
	s_waitcnt lgkmcnt(2)
	v_cvt_pk_bf16_f32 v52, v64, v78
	s_waitcnt lgkmcnt(0)
	v_cvt_pk_bf16_f32 v53, v80, v82
	v_mul_u32_u24_e32 v0, 0x1600, v0
	global_store_dwordx4 v[84:85], v[50:53], off
	v_lshl_add_u64 v[54:55], v[54:55], 0, v[0:1]
	s_nop 0
	v_cvt_pk_bf16_f32 v50, v57, v59
	v_cvt_pk_bf16_f32 v51, v61, v63
	v_cvt_pk_bf16_f32 v52, v65, v79
	v_cvt_pk_bf16_f32 v53, v81, v83
	global_store_dwordx4 v[54:55], v[50:53], off
	s_waitcnt lgkmcnt(0)

; #define LAS __attribute__((address_space(3)))
; #define LDS_WAIT() asm volatile("s_waitcnt lgkmcnt(0)" ::: "memory")
; __device__ __forceinline__ void tr_item(const float* W, int ldw, int src_col, int nvalid, int k0, bf16_t* WT, int ldt, int dst_row, int dst_k, LAS float* scr, int lane) {
; #pragma unroll 8
;     for (int i = 0; i < 32; ++i) { const int kk = 2 * i + (lane >> 5), c = lane & 31; scr[kk * 33 + c] = (c < nvalid) ? W[(size_t)(k0 + kk) * ldw + src_col + c] : 0.f; }
;     LDS_WAIT();
.LBB0_1495:
	s_lshl_b32 s16, s10, 1
	s_lshl_b32 s13, s6, 1
	v_or_b32_e32 v49, s16, v2
	v_or_b32_e32 v0, s13, v3
	v_add_u32_e32 v52, s12, v49
	v_add_u32_e32 v54, s3, v0
	v_mad_i64_i32 v[52:53], s[18:19], v52, s54, v[50:51]
	v_mad_i64_i32 v[54:55], s[18:19], v54, s54, v[50:51]
	global_load_dword v132, v[52:53], off
	global_load_dword v133, v[54:55], off
	v_mad_u64_u32 v[52:53], s[18:19], v49, s53, v[6:7]
	v_mad_u64_u32 v[54:55], s[18:19], v0, s53, v[6:7]
	s_add_i32 s18, s16, 4
	s_add_i32 s17, s13, 4
	v_or_b32_e32 v49, s18, v2
	v_or_b32_e32 v0, s17, v3
	s_add_i32 s17, s13, 8
	s_add_i32 s10, s10, 16
	s_add_i32 s6, s6, 16
	s_add_i32 s11, s11, -16
	v_mov_b32_e32 v148, v52
	v_mov_b32_e32 v149, v54
	v_add_u32_e32 v52, s12, v49
	v_add_u32_e32 v54, s3, v0
	v_mad_i64_i32 v[52:53], s[18:19], v52, s54, v[50:51]
	v_mad_i64_i32 v[54:55], s[18:19], v54, s54, v[50:51]
	global_load_dword v134, v[52:53], off
	global_load_dword v135, v[54:55], off
	v_mad_u64_u32 v[52:53], s[18:19], v49, s53, v[6:7]
	v_mad_u64_u32 v[54:55], s[18:19], v0, s53, v[6:7]
	s_add_i32 s18, s16, 8
	s_nop 0
	v_or_b32_e32 v49, s18, v2
	v_or_b32_e32 v0, s17, v3
	s_add_i32 s17, s13, 12
	v_mov_b32_e32 v150, v52
	v_mov_b32_e32 v151, v54
	v_add_u32_e32 v52, s12, v49
	v_add_u32_e32 v54, s3, v0
	v_mad_i64_i32 v[52:53], s[18:19], v52, s54, v[50:51]
	v_mad_i64_i32 v[54:55], s[18:19], v54, s54, v[50:51]
	global_load_dword v136, v[52:53], off
	global_load_dword v137, v[54:55], off
	v_mad_u64_u32 v[52:53], s[18:19], v49, s53, v[6:7]
	v_mad_u64_u32 v[54:55], s[18:19], v0, s53, v[6:7]
	s_add_i32 s18, s16, 12
	s_nop 0
	v_or_b32_e32 v49, s18, v2
	v_or_b32_e32 v0, s17, v3
	s_add_i32 s17, s13, 16
	v_mov_b32_e32 v152, v52
	v_mov_b32_e32 v153, v54
	v_add_u32_e32 v52, s12, v49
	v_add_u32_e32 v54, s3, v0
	v_mad_i64_i32 v[52:53], s[18:19], v52, s54, v[50:51]
	v_mad_i64_i32 v[54:55], s[18:19], v54, s54, v[50:51]
	global_load_dword v138, v[52:53], off
	global_load_dword v139, v[54:55], off
	v_mad_u64_u32 v[52:53], s[18:19], v49, s53, v[6:7]
	v_mad_u64_u32 v[54:55], s[18:19], v0, s53, v[6:7]
	s_add_i32 s18, s16, 16
	s_nop 0
	v_or_b32_e32 v49, s18, v2
	v_or_b32_e32 v0, s17, v3
	s_add_i32 s17, s13, 20
	v_mov_b32_e32 v154, v52
	v_mov_b32_e32 v155, v54
	v_add_u32_e32 v52, s12, v49
	v_add_u32_e32 v54, s3, v0
	v_mad_i64_i32 v[52:53], s[18:19], v52, s54, v[50:51]
	v_mad_i64_i32 v[54:55], s[18:19], v54, s54, v[50:51]
	global_load_dword v140, v[52:53], off
	global_load_dword v141, v[54:55], off
	v_mad_u64_u32 v[52:53], s[18:19], v49, s53, v[6:7]
	v_mad_u64_u32 v[54:55], s[18:19], v0, s53, v[6:7]
	s_add_i32 s18, s16, 20
	s_nop 0
	v_or_b32_e32 v49, s18, v2
	v_or_b32_e32 v0, s17, v3
	s_add_i32 s17, s13, 24
	s_add_i32 s13, s13, 28
	v_mov_b32_e32 v156, v52
	v_mov_b32_e32 v157, v54
	v_add_u32_e32 v52, s12, v49
	v_add_u32_e32 v54, s3, v0
	v_mad_i64_i32 v[52:53], s[18:19], v52, s54, v[50:51]
	v_mad_i64_i32 v[54:55], s[18:19], v54, s54, v[50:51]
	global_load_dword v142, v[52:53], off
	global_load_dword v143, v[54:55], off
	v_mad_u64_u32 v[52:53], s[18:19], v49, s53, v[6:7]
	v_mad_u64_u32 v[54:55], s[18:19], v0, s53, v[6:7]
	s_add_i32 s18, s16, 24
	s_nop 0
	v_or_b32_e32 v49, s18, v2
	v_or_b32_e32 v0, s17, v3
	s_add_i32 s16, s16, 28
	s_cmp_lg_u32 s11, 0
	v_mov_b32_e32 v158, v52
	v_mov_b32_e32 v159, v54
	v_add_u32_e32 v52, s12, v49
	v_add_u32_e32 v54, s3, v0
	v_mad_i64_i32 v[52:53], s[18:19], v52, s54, v[50:51]
	v_mad_i64_i32 v[54:55], s[18:19], v54, s54, v[50:51]
	global_load_dword v144, v[52:53], off
	global_load_dword v145, v[54:55], off
	v_mad_u64_u32 v[52:53], s[18:19], v49, s53, v[6:7]
	v_or_b32_e32 v49, s16, v2
	v_mad_u64_u32 v[54:55], s[18:19], v0, s53, v[6:7]
	v_or_b32_e32 v0, s13, v3
	v_mov_b32_e32 v160, v52
	v_mov_b32_e32 v161, v54
	v_add_u32_e32 v52, s12, v49
	v_add_u32_e32 v54, s3, v0
	v_mad_i64_i32 v[52:53], s[16:17], v52, s54, v[50:51]
	v_mad_i64_i32 v[54:55], s[16:17], v54, s54, v[50:51]
	global_load_dword v146, v[52:53], off
	global_load_dword v147, v[54:55], off
	v_mad_u64_u32 v[52:53], s[16:17], v49, s53, v[6:7]
	v_mad_u64_u32 v[54:55], s[16:17], v0, s53, v[6:7]
	v_mov_b32_e32 v162, v52
	v_mov_b32_e32 v163, v54
	s_waitcnt vmcnt(15)
	ds_write_b32 v148, v132
	s_waitcnt vmcnt(14)
	ds_write_b32 v149, v133
	s_waitcnt vmcnt(13)
	ds_write_b32 v150, v134
	s_waitcnt vmcnt(12)
	ds_write_b32 v151, v135
	s_waitcnt vmcnt(11)
	ds_write_b32 v152, v136
	s_waitcnt vmcnt(10)
	ds_write_b32 v153, v137
	s_waitcnt vmcnt(9)
	ds_write_b32 v154, v138
	s_waitcnt vmcnt(8)
	ds_write_b32 v155, v139
	s_waitcnt vmcnt(7)
	ds_write_b32 v156, v140
	s_waitcnt vmcnt(6)
	ds_write_b32 v157, v141
	s_waitcnt vmcnt(5)
	ds_write_b32 v158, v142
	s_waitcnt vmcnt(4)
	ds_write_b32 v159, v143
	s_waitcnt vmcnt(3)
	ds_write_b32 v160, v144
	s_waitcnt vmcnt(2)
	ds_write_b32 v161, v145
	s_waitcnt vmcnt(1)
	ds_write_b32 v162, v146
	s_waitcnt vmcnt(0)
	ds_write_b32 v163, v147
	s_cbranch_scc1 .LBB0_1495
; #define LAS __attribute__((address_space(3)))
; __device__ __forceinline__ unsigned cvt_pk_bf16(float lo, float hi) { f32x2_t v = {lo, hi}; bf16x2_t b = __builtin_convertvector(v, bf16x2_t); return __builtin_bit_cast(unsigned, b); }
; #define LDS_WAIT() asm volatile("s_waitcnt lgkmcnt(0)" ::: "memory")
; __device__ __forceinline__ void tr_item(const float* W, int ldw, int src_col, int nvalid, int k0, bf16_t* WT, int ldt, int dst_row, int dst_k, LAS float* scr, int lane) {
;     ...
;     LDS_WAIT();
;     const int c = lane & 7;
; #pragma unroll
;     for (int j = 0; j < 4; ++j) { const int n = (lane >> 3) + 8 * j; const LAS float* s = scr + (8 * c) * 33 + n;
;         u32x4 o; o.x = cvt_pk_bf16(s[0 * 33], s[1 * 33]); o.y = cvt_pk_bf16(s[2 * 33], s[3 * 33]); o.z = cvt_pk_bf16(s[4 * 33], s[5 * 33]); o.w = cvt_pk_bf16(s[6 * 33], s[7 * 33]);
;         *(u32x4*)(WT + (size_t)(dst_row + n) * ldt + dst_k + k0 + 8 * c) = o; }
;     LDS_WAIT();
	s_waitcnt lgkmcnt(0)
	ds_read2_b32 v[56:57], v7 offset0:33 offset1:41
	ds_read2_b32 v[58:59], v7 offset1:8
	ds_read2_b32 v[60:61], v7 offset0:66 offset1:74
	ds_read2_b32 v[62:63], v7 offset0:99 offset1:107
	ds_read2_b32 v[64:65], v7 offset0:132 offset1:140
	ds_read2_b32 v[78:79], v7 offset0:165 offset1:173
	ds_read2_b32 v[80:81], v7 offset0:198 offset1:206
	ds_read2_b32 v[82:83], v7 offset0:231 offset1:239
	v_or_b32_e32 v84, s2, v5
	s_ashr_i32 s13, s12, 31
	v_ashrrev_i32_e32 v85, 31, v84
	v_lshl_add_u64 v[54:55], s[12:13], 1, v[8:9]
	v_lshlrev_b64 v[84:85], 11, v[84:85]
	s_waitcnt lgkmcnt(6)
	v_cvt_pk_bf16_f32 v50, v58, v56
	s_waitcnt lgkmcnt(4)
	v_cvt_pk_bf16_f32 v51, v60, v62
	s_waitcnt lgkmcnt(2)
	v_cvt_pk_bf16_f32 v52, v64, v78
	s_waitcnt lgkmcnt(0)
	v_cvt_pk_bf16_f32 v53, v80, v82
	v_lshl_add_u64 v[84:85], v[54:55], 0, v[84:85]
	v_or_b32_e32 v56, s2, v35
	global_store_dwordx4 v[84:85], v[50:53], off
	v_or_b32_e32 v84, s2, v67
	v_ashrrev_i32_e32 v85, 31, v84
	v_cvt_pk_bf16_f32 v50, v59, v57
	v_ashrrev_i32_e32 v57, 31, v56
	v_lshlrev_b64 v[56:57], 11, v[56:57]
	v_cvt_pk_bf16_f32 v51, v61, v63
	v_cvt_pk_bf16_f32 v52, v65, v79
	v_cvt_pk_bf16_f32 v53, v81, v83
	v_lshl_add_u64 v[56:57], v[54:55], 0, v[56:57]
	global_store_dwordx4 v[56:57], v[50:53], off
	ds_read2_b32 v[56:57], v7 offset0:49 offset1:57
	ds_read2_b32 v[58:59], v7 offset0:16 offset1:24
	ds_read2_b32 v[60:61], v7 offset0:82 offset1:90
	ds_read2_b32 v[62:63], v7 offset0:115 offset1:123
	ds_read2_b32 v[64:65], v7 offset0:148 offset1:156
	ds_read2_b32 v[78:79], v7 offset0:181 offset1:189
	ds_read2_b32 v[80:81], v7 offset0:214 offset1:222
	ds_read2_b32 v[82:83], v7 offset0:247 offset1:255
	v_lshlrev_b64 v[84:85], 11, v[84:85]
	s_waitcnt lgkmcnt(6)
	v_cvt_pk_bf16_f32 v50, v58, v56
	s_waitcnt lgkmcnt(4)
	v_cvt_pk_bf16_f32 v51, v60, v62
	s_waitcnt lgkmcnt(2)
	v_cvt_pk_bf16_f32 v52, v64, v78
	s_waitcnt lgkmcnt(0)
	v_cvt_pk_bf16_f32 v53, v80, v82
	v_lshl_add_u64 v[84:85], v[54:55], 0, v[84:85]
	v_or_b32_e32 v56, s2, v68
	global_store_dwordx4 v[84:85], v[50:53], off
	s_nop 1
	v_cvt_pk_bf16_f32 v50, v59, v57
	v_ashrrev_i32_e32 v57, 31, v56
	v_lshlrev_b64 v[56:57], 11, v[56:57]
	v_cvt_pk_bf16_f32 v51, v61, v63
	v_cvt_pk_bf16_f32 v52, v65, v79
	v_cvt_pk_bf16_f32 v53, v81, v83
	v_lshl_add_u64 v[54:55], v[54:55], 0, v[56:57]
	global_store_dwordx4 v[54:55], v[50:53], off
	s_waitcnt lgkmcnt(0)
	s_branch .LBB0_1410

; __device__ __forceinline__ void convert_layer(const Ctx& C, int l) {
;     ...
;     {
;         float* cb = (float*)(ws + WS_CBP) + (size_t)l * 64 * 256;
;         for (int it = C.gw; it < 64; it += C.NGW) {
;             const int kv = it >> 5, ch = it & 31;
;             const float* pos = kv ? INF(13, l, 2048) : INF(12, l, 2048);
;             const float* w1 = kv ? INF(17, l, 2048 * 256) : INF(14, l, 2048 * 256);
;             float p[4] = {0.f, 0.f, 0.f, 0.f};
;             for (int k = ch * 64; k < ch * 64 + 64; ++k) { const float pv = pos[k];
; #pragma unroll
;                 for (int q = 0; q < 4; ++q) p[q] += pv * w1[(size_t)k * 256 + lane + 64 * q]; }
; #pragma unroll
;             for (int q = 0; q < 4; ++q) cb[(size_t)it * 256 + lane + 64 * q] = p[q];
;         }
;     }
.LBB0_1503:
	v_lshl_add_u64 v[18:19], v[8:9], 0, s[12:13]
	v_add_co_u32_e32 v20, vcc, 0x200000, v18
	global_load_dwordx4 v[2:5], v1, s[0:1] offset:-12
	global_load_dwordx4 v[14:17], v1, s[0:1] offset:-28
	v_addc_co_u32_e32 v21, vcc, 0, v19, vcc
	s_mov_b32 s3, 0x201000
	v_add_co_u32_e32 v22, vcc, s3, v18
	s_nop 1
	v_addc_co_u32_e32 v23, vcc, 0, v19, vcc
	global_load_dword v132, v[20:21], off
	global_load_dword v133, v[20:21], off offset:256
	global_load_dword v134, v[20:21], off offset:512
	global_load_dword v135, v[20:21], off offset:768
	global_load_dword v136, v[20:21], off offset:1024
	global_load_dword v137, v[20:21], off offset:1280
	global_load_dword v138, v[20:21], off offset:1536
	global_load_dword v139, v[20:21], off offset:1792
	global_load_dword v140, v[20:21], off offset:2048
	global_load_dword v141, v[20:21], off offset:2304
	global_load_dword v142, v[20:21], off offset:2560
	global_load_dword v143, v[20:21], off offset:2816
	global_load_dword v144, v[20:21], off offset:3072
	global_load_dword v145, v[20:21], off offset:3328
	global_load_dword v146, v[20:21], off offset:3584
	global_load_dword v147, v[20:21], off offset:3840
	global_load_dword v148, v[22:23], off
	global_load_dword v149, v[22:23], off offset:256
	global_load_dword v150, v[22:23], off offset:512
	global_load_dword v151, v[22:23], off offset:768
	global_load_dword v152, v[22:23], off offset:1024
	global_load_dword v153, v[22:23], off offset:1280
	global_load_dword v154, v[22:23], off offset:1536
	global_load_dword v155, v[22:23], off offset:1792
	global_load_dword v156, v[22:23], off offset:2048
	global_load_dword v157, v[22:23], off offset:2304
	global_load_dword v158, v[22:23], off offset:2560
	global_load_dword v159, v[22:23], off offset:2816
	global_load_dword v160, v[22:23], off offset:3072
	global_load_dword v161, v[22:23], off offset:3328
	global_load_dword v162, v[22:23], off offset:3584
	global_load_dword v163, v[22:23], off offset:3840
	s_add_u32 s12, s12, 0x2000
	s_addc_u32 s13, s13, 0
	s_add_u32 s0, s0, 32
	s_addc_u32 s1, s1, 0
	s_cmp_eq_u32 s12, 0x10000
	s_waitcnt vmcnt(30)
	v_pk_fma_f32 v[10:11], v[14:15], v[132:133], v[10:11] op_sel_hi:[0,1,1]
	s_waitcnt vmcnt(28)
	v_pk_fma_f32 v[12:13], v[14:15], v[134:135], v[12:13] op_sel_hi:[0,1,1]
	s_waitcnt vmcnt(26)
	v_pk_fma_f32 v[10:11], v[14:15], v[136:137], v[10:11] op_sel:[1,0,0]
	s_waitcnt vmcnt(24)
	v_pk_fma_f32 v[12:13], v[14:15], v[138:139], v[12:13] op_sel:[1,0,0]
	s_waitcnt vmcnt(22)
	v_pk_fma_f32 v[10:11], v[16:17], v[140:141], v[10:11] op_sel_hi:[0,1,1]
	s_waitcnt vmcnt(20)
	v_pk_fma_f32 v[12:13], v[16:17], v[142:143], v[12:13] op_sel_hi:[0,1,1]
	s_waitcnt vmcnt(18)
	v_pk_fma_f32 v[10:11], v[16:17], v[144:145], v[10:11] op_sel:[1,0,0]
	s_waitcnt vmcnt(16)
	v_pk_fma_f32 v[12:13], v[16:17], v[146:147], v[12:13] op_sel:[1,0,0]
	s_waitcnt vmcnt(14)
	v_pk_fma_f32 v[10:11], v[2:3], v[148:149], v[10:11] op_sel_hi:[0,1,1]
	s_waitcnt vmcnt(12)
	v_pk_fma_f32 v[12:13], v[2:3], v[150:151], v[12:13] op_sel_hi:[0,1,1]
	s_waitcnt vmcnt(10)
	v_pk_fma_f32 v[10:11], v[2:3], v[152:153], v[10:11] op_sel:[1,0,0]
	s_waitcnt vmcnt(8)
	v_pk_fma_f32 v[12:13], v[2:3], v[154:155], v[12:13] op_sel:[1,0,0]
	s_waitcnt vmcnt(6)
	v_pk_fma_f32 v[10:11], v[4:5], v[156:157], v[10:11] op_sel_hi:[0,1,1]
	s_waitcnt vmcnt(4)
	v_pk_fma_f32 v[12:13], v[4:5], v[158:159], v[12:13] op_sel_hi:[0,1,1]
	s_waitcnt vmcnt(2)
	v_pk_fma_f32 v[10:11], v[4:5], v[160:161], v[10:11] op_sel:[1,0,0]
	s_waitcnt vmcnt(0)
	v_pk_fma_f32 v[12:13], v[4:5], v[162:163], v[12:13] op_sel:[1,0,0]
	s_cbranch_scc0 .LBB0_1503
	s_ashr_i32 s35, s34, 31
	s_lshl_b64 s[0:1], s[34:35], 10
	s_add_i32 s34, s34, s70
	s_add_i32 s2, s2, s10
	v_lshl_add_u64 v[2:3], v[6:7], 0, s[0:1]
	s_cmp_gt_i32 s34, 63
	global_store_dword v[2:3], v10, off
	global_store_dword v[2:3], v11, off offset:256
	global_store_dword v[2:3], v12, off offset:512
	global_store_dword v[2:3], v13, off offset:768
	s_cbranch_scc0 .LBB0_1502
	v_readlane_b32 s40, v254, 0
	v_readlane_b32 s44, v254, 48
	v_readlane_b32 s50, v254, 53
	v_readlane_b32 s42, v253, 46
	v_readlane_b32 s41, v254, 1
	v_readlane_b32 s43, v254, 47
	v_readlane_b32 s45, v254, 49
	v_readlane_b32 s46, v254, 50
	v_readlane_b32 s48, v254, 51
	v_readlane_b32 s51, v254, 54
	v_readlane_b32 s47, v254, 55
	v_readlane_b32 s26, v254, 56
	v_readlane_b32 s20, v254, 57
	v_readlane_b32 s21, v254, 58
	v_readlane_b32 s27, v254, 59
	v_readlane_b32 s36, v254, 62
	v_readlane_b32 s49, v254, 52
